# scan: chunk barrier moved before the last 1.3 steps; next chunk step-0 operands prefetched into a third register set across the barrier
# baseline (speedup 1.0000x reference)
; #define LAS __attribute__((address_space(3)))
; __global__ void __launch_bounds__(512, 2) fwd_megakernel(Params P) {
;     ...
;                         const int row = half * 32 + wid * 8 + rg;
;                         f32x2 Sa = {0.f, 0.f}, Sb = {0.f, 0.f}, Sc = {0.f, 0.f}, Sd = {0.f, 0.f};
;                         f16* yout = Y16 + m0 * 1024 + h * 64 + row;
;                         __builtin_amdgcn_s_setprio(3);
;                         __syncthreads();
; #pragma unroll 1
;                         for (int c = 0; c < T / 32; ++c) {
;                             const LAS unsigned char* buf = lds + (c & 1) * 41984;
;                             const LAS unsigned char* pk = buf + kq * 32; const LAS unsigned char* pv = buf + 1024 + row * 4;
;     ...
;                             f32x4 rg2[2][8]; float rv2[2];
;                             SCAN_LOAD(rg2[0], rv2[0], 0);
; #pragma unroll
;                             for (int tt = 0; tt < 32; tt += 8) {
;                                 float yk = 0.f;
;                                 const f32x4 ge0 = *(const LAS f32x4*)(pk + 40960 + (tt >> 3) * 256), ge1 = *(const LAS f32x4*)(pk + 40960 + (tt >> 3) * 256 + 16);
; #pragma unroll
;                                 for (int j = 0; j < 8; ++j) {
;                                     if (j < 7 || tt + 8 < 32) SCAN_LOAD(rg2[(j + 1) & 1], rv2[(j + 1) & 1], tt + j + 1);
;                                     __builtin_amdgcn_sched_barrier(0);
;                                     const f32x4 (&cur)[8] = rg2[j & 1]; const float curv = rv2[j & 1];
;                                     const f32x2 v2 = {curv, curv};
;                                     const f32x2 pa = v2 * cur[4].xy + Sa, pb = v2 * cur[4].zw + Sb, pc = v2 * cur[5].xy + Sc, pd = v2 * cur[5].zw + Sd;
;                                     f32x2 t0 = Sa * cur[0].xy; t0 = Sb * cur[0].zw + t0;
;                                     f32x2 t1 = Sc * cur[1].xy; t1 = Sd * cur[1].zw + t1;
;                                     const f32x2 t = t0 + t1;
;                                     float sa = sum8(t.x + t.y);
;                                     const f32x2 sa2 = {sa, sa};
;                                     Sa = sa2 * cur[2].xy + pa; Sb = sa2 * cur[2].zw + pb; Sc = sa2 * cur[3].xy + pc; Sd = sa2 * cur[3].zw + pd;
.LBB0_249:
	s_ashr_i32 s92, s3, 5
	s_bfe_u32 s40, s3, 0x40001
	s_and_b32 s39, s3, 1
	s_ashr_i32 s93, s92, 31
	s_mov_b64 s[62:63], -1
	s_and_b64 vcc, exec, s[36:37]
	s_cbranch_vccz .LBB0_253
	v_cndmask_b32_e64 v1, 0, 1, s[90:91]
	v_lshl_add_u32 v2, v1, 5, v180
	s_lshl_b32 s46, s40, 7
	v_ashrrev_i32_e32 v3, 31, v2
	s_lshl_b32 s47, s39, 5
	s_lshl_b64 s[44:45], s[92:93], 23
	s_setprio 3
	s_or_b32 s44, s44, s46
	s_waitcnt vmcnt(21)
	v_mov_b32_e32 v8, s44
	v_mov_b32_e32 v9, s45
	v_lshl_add_u64 v[2:3], v[2:3], 1, v[8:9]
	s_waitcnt vmcnt(19)
	v_mov_b32_e32 v18, 0
	v_add_lshl_u32 v1, s47, v180, 2
	v_lshl_add_u64 v[2:3], v[134:135], 0, v[2:3]
	s_mov_b32 s46, 0
	s_mov_b64 s[94:95], 0
	v_mov_b32_e32 v19, v18
	s_waitcnt vmcnt(18)
	v_mov_b32_e32 v20, v18
	v_mov_b32_e32 v21, v18
	v_mov_b32_e32 v22, v18
	v_mov_b32_e32 v23, v18
	s_waitcnt vmcnt(17)
	v_mov_b32_e32 v24, v18
	v_mov_b32_e32 v25, v18
	s_waitcnt vmcnt(0)
	s_or_b64 s[44:45], s[14:15], s[18:19]
	s_or_b64 s[44:45], s[44:45], s[22:23]
	s_or_b64 s[44:45], s[44:45], s[26:27]
	s_or_b64 s[100:101], s[16:17], s[18:19]
	s_or_b64 s[100:101], s[100:101], s[24:25]
	s_or_b64 s[100:101], s[100:101], s[26:27]
	s_mov_b32 s46, 0x24000000
	v_mov_b32_e32 v26, v181
	v_mov_b32_e32 v27, v1
	v_add_co_u32_e32 v98, vcc, s46, v2
	s_nop 1
	v_addc_co_u32_e32 v99, vcc, 0, v3, vcc
	v_readfirstlane_b32 s46, v180
	s_nop 3
	s_lshr_b32 s46, s46, 3
	s_barrier
	ds_read_b128 v[140:143], v26 offset:0
	ds_read_b128 v[144:147], v26 offset:16
	ds_read_b128 v[156:159], v26 offset:512
	ds_read_b128 v[160:163], v26 offset:528
	ds_read_b32 v172, v27 offset:1024
	ds_read_b128 v[148:151], v26 offset:256
	ds_read_b128 v[152:155], v26 offset:272
	ds_read_b128 v[164:167], v26 offset:768
	ds_read_b128 v[168:171], v26 offset:784
.Lscan_chunk:
	ds_read_b128 v[64:67], v26 offset:1280
	ds_read_b128 v[68:71], v26 offset:1296
	ds_read_b128 v[80:83], v26 offset:1792
	ds_read_b128 v[84:87], v26 offset:1808
	ds_read_b32 v96, v27 offset:2304
	ds_read_b128 v[72:75], v26 offset:1536
	ds_read_b128 v[76:79], v26 offset:1552
	ds_read_b128 v[88:91], v26 offset:2048
	ds_read_b128 v[92:95], v26 offset:2064
	s_waitcnt lgkmcnt(9)
	v_pk_mul_f32 v[8:9], v[18:19], v[140:141]
	ds_read_b128 v[124:127], v26 offset:40960
	v_pk_fma_f32 v[8:9], v[20:21], v[142:143], v[8:9]
	ds_read_b128 v[128:131], v26 offset:40976
	v_pk_fma_f32 v[8:9], v[22:23], v[144:145], v[8:9]
	v_pk_fma_f32 v[116:117], v[172:173], v[156:157], v[18:19] op_sel_hi:[0,1,1]
	v_pk_fma_f32 v[8:9], v[24:25], v[146:147], v[8:9]
	v_pk_fma_f32 v[118:119], v[172:173], v[158:159], v[20:21] op_sel_hi:[0,1,1]
	v_add_f32_e32 v8, v8, v9
	v_pk_fma_f32 v[120:121], v[172:173], v[160:161], v[22:23] op_sel_hi:[0,1,1]
	v_pk_fma_f32 v[122:123], v[172:173], v[162:163], v[24:25] op_sel_hi:[0,1,1]
	v_add_f32_dpp v8, v8, v8 quad_perm:[1,0,3,2] row_mask:0xf bank_mask:0xf bound_ctrl:1
	ds_read_b128 v[28:31], v26 offset:2560
	ds_read_b128 v[32:35], v26 offset:2576
	v_add_f32_dpp v8, v8, v8 quad_perm:[2,3,0,1] row_mask:0xf bank_mask:0xf bound_ctrl:1
	ds_read_b128 v[44:47], v26 offset:3072
	ds_read_b128 v[48:51], v26 offset:3088
	v_add_f32_dpp v8, v8, v8 row_half_mirror row_mask:0xf bank_mask:0xf bound_ctrl:1
	ds_read_b32 v60, v27 offset:3584
	v_pk_fma_f32 v[18:19], v[148:149], v[8:9], v[116:117] op_sel_hi:[1,0,1]
	v_pk_fma_f32 v[20:21], v[150:151], v[8:9], v[118:119] op_sel_hi:[1,0,1]
	s_waitcnt lgkmcnt(12)
	v_pk_mul_f32 v[10:11], v[18:19], v[64:65]
	v_pk_fma_f32 v[22:23], v[152:153], v[8:9], v[120:121] op_sel_hi:[1,0,1]
	v_pk_fma_f32 v[10:11], v[20:21], v[66:67], v[10:11]
	v_pk_fma_f32 v[24:25], v[154:155], v[8:9], v[122:123] op_sel_hi:[1,0,1]
	v_pk_fma_f32 v[10:11], v[22:23], v[68:69], v[10:11]
	s_waitcnt lgkmcnt(7)
	v_pk_fma_f32 v[116:117], v[96:97], v[80:81], v[18:19] op_sel_hi:[0,1,1]
	v_pk_fma_f32 v[10:11], v[24:25], v[70:71], v[10:11]
	v_pk_fma_f32 v[118:119], v[96:97], v[82:83], v[20:21] op_sel_hi:[0,1,1]
	v_add_f32_e32 v10, v10, v11
	v_pk_fma_f32 v[120:121], v[96:97], v[84:85], v[22:23] op_sel_hi:[0,1,1]
	v_pk_fma_f32 v[122:123], v[96:97], v[86:87], v[24:25] op_sel_hi:[0,1,1]
	v_add_f32_dpp v10, v10, v10 quad_perm:[1,0,3,2] row_mask:0xf bank_mask:0xf bound_ctrl:1
	v_pk_mul_f32 v[12:13], v[164:165], v[18:19]
	ds_read_b128 v[36:39], v26 offset:2816
	v_add_f32_dpp v10, v10, v10 quad_perm:[2,3,0,1] row_mask:0xf bank_mask:0xf bound_ctrl:1
	v_pk_fma_f32 v[12:13], v[166:167], v[20:21], v[12:13]
	ds_read_b128 v[40:43], v26 offset:2832
	v_add_f32_dpp v10, v10, v10 row_half_mirror row_mask:0xf bank_mask:0xf bound_ctrl:1
	v_pk_fma_f32 v[12:13], v[168:169], v[22:23], v[12:13]
	ds_read_b128 v[64:67], v26 offset:3840
	v_pk_fma_f32 v[12:13], v[170:171], v[24:25], v[12:13]
	ds_read_b128 v[52:55], v26 offset:3328
	v_add_f32_e32 v100, v12, v13
	ds_read_b128 v[56:59], v26 offset:3344
	ds_read_b128 v[68:71], v26 offset:3856
	v_pk_fma_f32 v[18:19], v[72:73], v[10:11], v[116:117] op_sel_hi:[1,0,1]
	v_pk_fma_f32 v[20:21], v[74:75], v[10:11], v[118:119] op_sel_hi:[1,0,1]
	s_waitcnt lgkmcnt(6)
; #define LAS __attribute__((address_space(3)))
; __device__ __forceinline__ float sum8(float x) { x += dppf<0xB1>(x); x += dppf<0x4E>(x); x += dppf<0x141>(x); return x; }
; __global__ void __launch_bounds__(512, 2) fwd_megakernel(Params P) {
;     ...
;                             for (int tt = 0; tt < 32; tt += 8) {
;                                 float yk = 0.f;
;                                 const f32x4 ge0 = *(const LAS f32x4*)(pk + 40960 + (tt >> 3) * 256), ge1 = *(const LAS f32x4*)(pk + 40960 + (tt >> 3) * 256 + 16);
; #pragma unroll
;                                 for (int j = 0; j < 8; ++j) {
;                                     if (j < 7 || tt + 8 < 32) SCAN_LOAD(rg2[(j + 1) & 1], rv2[(j + 1) & 1], tt + j + 1);
;                                     __builtin_amdgcn_sched_barrier(0);
;                                     const f32x4 (&cur)[8] = rg2[j & 1]; const float curv = rv2[j & 1];
;                                     const f32x2 v2 = {curv, curv};
;                                     const f32x2 pa = v2 * cur[4].xy + Sa, pb = v2 * cur[4].zw + Sb, pc = v2 * cur[5].xy + Sc, pd = v2 * cur[5].zw + Sd;
;                                     f32x2 t0 = Sa * cur[0].xy; t0 = Sb * cur[0].zw + t0;
;                                     f32x2 t1 = Sc * cur[1].xy; t1 = Sd * cur[1].zw + t1;
;                                     const f32x2 t = t0 + t1;
;                                     float sa = sum8(t.x + t.y);
;                                     const f32x2 sa2 = {sa, sa};
;                                     Sa = sa2 * cur[2].xy + pa; Sb = sa2 * cur[2].zw + pb; Sc = sa2 * cur[3].xy + pc; Sd = sa2 * cur[3].zw + pd;
;                                     f32x2 u0 = Sa * cur[6].xy; u0 = Sb * cur[6].zw + u0;
;                                     f32x2 u1 = Sc * cur[7].xy; u1 = Sd * cur[7].zw + u1;
;                                     const f32x2 u = u0 + u1;
;                                     const float y = sum8(u.x + u.y);
;                                     yk = (kq == j) ? y : yk;
;                                 }
;                                 Sa *= ge0.xy; Sb *= ge0.zw; Sc *= ge1.xy; Sd *= ge1.zw;
;                                 yout[(size_t)(c * 32 + tt + kq) * 1024] = (f16)yk;
	v_pk_mul_f32 v[8:9], v[18:19], v[28:29]
	v_pk_fma_f32 v[22:23], v[76:77], v[10:11], v[120:121] op_sel_hi:[1,0,1]
	v_pk_fma_f32 v[8:9], v[20:21], v[30:31], v[8:9]
	v_pk_fma_f32 v[24:25], v[78:79], v[10:11], v[122:123] op_sel_hi:[1,0,1]
	v_pk_fma_f32 v[8:9], v[22:23], v[32:33], v[8:9]
	ds_read_b128 v[80:83], v26 offset:4352
	v_pk_fma_f32 v[8:9], v[24:25], v[34:35], v[8:9]
	ds_read_b128 v[84:87], v26 offset:4368
	v_add_f32_e32 v8, v8, v9
	ds_read_b32 v96, v27 offset:4864
	v_pk_fma_f32 v[116:117], v[60:61], v[44:45], v[18:19] op_sel_hi:[0,1,1]
	v_add_f32_dpp v8, v8, v8 quad_perm:[1,0,3,2] row_mask:0xf bank_mask:0xf bound_ctrl:1
	v_pk_fma_f32 v[118:119], v[60:61], v[46:47], v[20:21] op_sel_hi:[0,1,1]
	v_pk_fma_f32 v[120:121], v[60:61], v[48:49], v[22:23] op_sel_hi:[0,1,1]
	v_add_f32_dpp v8, v8, v8 quad_perm:[2,3,0,1] row_mask:0xf bank_mask:0xf bound_ctrl:1
	v_pk_fma_f32 v[122:123], v[60:61], v[50:51], v[24:25] op_sel_hi:[0,1,1]
	v_pk_mul_f32 v[14:15], v[88:89], v[18:19]
	v_add_f32_dpp v8, v8, v8 row_half_mirror row_mask:0xf bank_mask:0xf bound_ctrl:1
	v_pk_fma_f32 v[14:15], v[90:91], v[20:21], v[14:15]
	ds_read_b128 v[72:75], v26 offset:4096
	v_pk_fma_f32 v[14:15], v[92:93], v[22:23], v[14:15]
	ds_read_b128 v[76:79], v26 offset:4112
	v_pk_fma_f32 v[14:15], v[94:95], v[24:25], v[14:15]
	ds_read_b128 v[88:91], v26 offset:4608
	v_add_f32_e32 v101, v14, v15
	ds_read_b128 v[92:95], v26 offset:4624
	v_add_f32_dpp v100, v100, v100 row_half_mirror row_mask:0xf bank_mask:0x5
	ds_read_b128 v[28:31], v26 offset:5120
	ds_read_b128 v[32:35], v26 offset:5136
	s_waitcnt lgkmcnt(9)
	v_pk_fma_f32 v[18:19], v[36:37], v[8:9], v[116:117] op_sel_hi:[1,0,1]
	v_pk_fma_f32 v[20:21], v[38:39], v[8:9], v[118:119] op_sel_hi:[1,0,1]
	v_pk_mul_f32 v[10:11], v[18:19], v[64:65]
	v_pk_fma_f32 v[22:23], v[40:41], v[8:9], v[120:121] op_sel_hi:[1,0,1]
	v_pk_fma_f32 v[10:11], v[20:21], v[66:67], v[10:11]
	v_pk_fma_f32 v[24:25], v[42:43], v[8:9], v[122:123] op_sel_hi:[1,0,1]
	v_pk_fma_f32 v[10:11], v[22:23], v[68:69], v[10:11]
	ds_read_b128 v[44:47], v26 offset:5632
	v_pk_fma_f32 v[10:11], v[24:25], v[70:71], v[10:11]
	ds_read_b128 v[48:51], v26 offset:5648
	v_add_f32_e32 v10, v10, v11
	ds_read_b32 v60, v27 offset:6144
	s_waitcnt lgkmcnt(9)
	v_pk_fma_f32 v[116:117], v[96:97], v[80:81], v[18:19] op_sel_hi:[0,1,1]
	v_add_f32_dpp v10, v10, v10 quad_perm:[1,0,3,2] row_mask:0xf bank_mask:0xf bound_ctrl:1
	v_pk_fma_f32 v[118:119], v[96:97], v[82:83], v[20:21] op_sel_hi:[0,1,1]
	v_pk_fma_f32 v[120:121], v[96:97], v[84:85], v[22:23] op_sel_hi:[0,1,1]
	v_add_f32_dpp v10, v10, v10 quad_perm:[2,3,0,1] row_mask:0xf bank_mask:0xf bound_ctrl:1
	v_pk_fma_f32 v[122:123], v[96:97], v[86:87], v[24:25] op_sel_hi:[0,1,1]
	v_pk_mul_f32 v[12:13], v[52:53], v[18:19]
	v_add_f32_dpp v10, v10, v10 row_half_mirror row_mask:0xf bank_mask:0xf bound_ctrl:1
	v_pk_fma_f32 v[12:13], v[54:55], v[20:21], v[12:13]
	ds_read_b128 v[36:39], v26 offset:5376
	v_pk_fma_f32 v[12:13], v[56:57], v[22:23], v[12:13]
	ds_read_b128 v[40:43], v26 offset:5392
	v_pk_fma_f32 v[12:13], v[58:59], v[24:25], v[12:13]
	ds_read_b128 v[52:55], v26 offset:5888
	v_add_f32_e32 v102, v12, v13
	ds_read_b128 v[56:59], v26 offset:5904
	v_add_f32_dpp v101, v101, v101 row_half_mirror row_mask:0xf bank_mask:0x5
	ds_read_b128 v[64:67], v26 offset:6400
	ds_read_b128 v[68:71], v26 offset:6416
	s_waitcnt lgkmcnt(9)
	v_pk_fma_f32 v[18:19], v[72:73], v[10:11], v[116:117] op_sel_hi:[1,0,1]
	v_pk_fma_f32 v[20:21], v[74:75], v[10:11], v[118:119] op_sel_hi:[1,0,1]
	v_pk_mul_f32 v[8:9], v[18:19], v[28:29]
	v_pk_fma_f32 v[22:23], v[76:77], v[10:11], v[120:121] op_sel_hi:[1,0,1]
	v_pk_fma_f32 v[8:9], v[20:21], v[30:31], v[8:9]
	v_pk_fma_f32 v[24:25], v[78:79], v[10:11], v[122:123] op_sel_hi:[1,0,1]
	v_pk_fma_f32 v[8:9], v[22:23], v[32:33], v[8:9]
	ds_read_b128 v[80:83], v26 offset:6912
	v_pk_fma_f32 v[8:9], v[24:25], v[34:35], v[8:9]
	ds_read_b128 v[84:87], v26 offset:6928
	v_add_f32_e32 v8, v8, v9
	ds_read_b32 v96, v27 offset:7424
	s_waitcnt lgkmcnt(9)
	v_pk_fma_f32 v[116:117], v[60:61], v[44:45], v[18:19] op_sel_hi:[0,1,1]
	v_add_f32_dpp v8, v8, v8 quad_perm:[1,0,3,2] row_mask:0xf bank_mask:0xf bound_ctrl:1
	v_pk_fma_f32 v[118:119], v[60:61], v[46:47], v[20:21] op_sel_hi:[0,1,1]
	v_pk_fma_f32 v[120:121], v[60:61], v[48:49], v[22:23] op_sel_hi:[0,1,1]
	v_add_f32_dpp v8, v8, v8 quad_perm:[2,3,0,1] row_mask:0xf bank_mask:0xf bound_ctrl:1
	v_pk_fma_f32 v[122:123], v[60:61], v[50:51], v[24:25] op_sel_hi:[0,1,1]
	v_pk_mul_f32 v[14:15], v[88:89], v[18:19]
	v_add_f32_dpp v8, v8, v8 row_half_mirror row_mask:0xf bank_mask:0xf bound_ctrl:1
	v_pk_fma_f32 v[14:15], v[90:91], v[20:21], v[14:15]
	ds_read_b128 v[72:75], v26 offset:6656
	v_pk_fma_f32 v[14:15], v[92:93], v[22:23], v[14:15]
	ds_read_b128 v[76:79], v26 offset:6672
	v_pk_fma_f32 v[14:15], v[94:95], v[24:25], v[14:15]
	ds_read_b128 v[88:91], v26 offset:7168
	v_add_f32_e32 v103, v14, v15
	ds_read_b128 v[92:95], v26 offset:7184
	v_add_f32_dpp v102, v102, v102 row_half_mirror row_mask:0xf bank_mask:0x5
	ds_read_b128 v[28:31], v26 offset:7680
	ds_read_b128 v[32:35], v26 offset:7696
	s_waitcnt lgkmcnt(9)
	v_pk_fma_f32 v[18:19], v[36:37], v[8:9], v[116:117] op_sel_hi:[1,0,1]
	v_pk_fma_f32 v[20:21], v[38:39], v[8:9], v[118:119] op_sel_hi:[1,0,1]
	v_pk_mul_f32 v[10:11], v[18:19], v[64:65]
	v_pk_fma_f32 v[22:23], v[40:41], v[8:9], v[120:121] op_sel_hi:[1,0,1]
	v_pk_fma_f32 v[10:11], v[20:21], v[66:67], v[10:11]
	v_pk_fma_f32 v[24:25], v[42:43], v[8:9], v[122:123] op_sel_hi:[1,0,1]
	v_pk_fma_f32 v[10:11], v[22:23], v[68:69], v[10:11]
	ds_read_b128 v[44:47], v26 offset:8192
	v_pk_fma_f32 v[10:11], v[24:25], v[70:71], v[10:11]
	ds_read_b128 v[48:51], v26 offset:8208
	v_add_f32_e32 v10, v10, v11
	ds_read_b32 v60, v27 offset:8704
	s_waitcnt lgkmcnt(9)
; #define LAS __attribute__((address_space(3)))
; __device__ __forceinline__ float sum8(float x) { x += dppf<0xB1>(x); x += dppf<0x4E>(x); x += dppf<0x141>(x); return x; }
; __global__ void __launch_bounds__(512, 2) fwd_megakernel(Params P) {
;     ...
;                             for (int tt = 0; tt < 32; tt += 8) {
;                                 float yk = 0.f;
;                                 const f32x4 ge0 = *(const LAS f32x4*)(pk + 40960 + (tt >> 3) * 256), ge1 = *(const LAS f32x4*)(pk + 40960 + (tt >> 3) * 256 + 16);
; #pragma unroll
;                                 for (int j = 0; j < 8; ++j) {
;                                     if (j < 7 || tt + 8 < 32) SCAN_LOAD(rg2[(j + 1) & 1], rv2[(j + 1) & 1], tt + j + 1);
;                                     __builtin_amdgcn_sched_barrier(0);
;                                     const f32x4 (&cur)[8] = rg2[j & 1]; const float curv = rv2[j & 1];
;                                     const f32x2 v2 = {curv, curv};
;                                     const f32x2 pa = v2 * cur[4].xy + Sa, pb = v2 * cur[4].zw + Sb, pc = v2 * cur[5].xy + Sc, pd = v2 * cur[5].zw + Sd;
;                                     f32x2 t0 = Sa * cur[0].xy; t0 = Sb * cur[0].zw + t0;
;                                     f32x2 t1 = Sc * cur[1].xy; t1 = Sd * cur[1].zw + t1;
;                                     const f32x2 t = t0 + t1;
;                                     float sa = sum8(t.x + t.y);
;                                     const f32x2 sa2 = {sa, sa};
;                                     Sa = sa2 * cur[2].xy + pa; Sb = sa2 * cur[2].zw + pb; Sc = sa2 * cur[3].xy + pc; Sd = sa2 * cur[3].zw + pd;
;                                     f32x2 u0 = Sa * cur[6].xy; u0 = Sb * cur[6].zw + u0;
;                                     f32x2 u1 = Sc * cur[7].xy; u1 = Sd * cur[7].zw + u1;
;                                     const f32x2 u = u0 + u1;
;                                     const float y = sum8(u.x + u.y);
;                                     yk = (kq == j) ? y : yk;
;                                 }
;                                 Sa *= ge0.xy; Sb *= ge0.zw; Sc *= ge1.xy; Sd *= ge1.zw;
;                                 yout[(size_t)(c * 32 + tt + kq) * 1024] = (f16)yk;
	v_pk_fma_f32 v[116:117], v[96:97], v[80:81], v[18:19] op_sel_hi:[0,1,1]
	v_add_f32_dpp v10, v10, v10 quad_perm:[1,0,3,2] row_mask:0xf bank_mask:0xf bound_ctrl:1
	v_pk_fma_f32 v[118:119], v[96:97], v[82:83], v[20:21] op_sel_hi:[0,1,1]
	v_pk_fma_f32 v[120:121], v[96:97], v[84:85], v[22:23] op_sel_hi:[0,1,1]
	v_add_f32_dpp v10, v10, v10 quad_perm:[2,3,0,1] row_mask:0xf bank_mask:0xf bound_ctrl:1
	v_pk_fma_f32 v[122:123], v[96:97], v[86:87], v[24:25] op_sel_hi:[0,1,1]
	v_pk_mul_f32 v[12:13], v[52:53], v[18:19]
	v_add_f32_dpp v10, v10, v10 row_half_mirror row_mask:0xf bank_mask:0xf bound_ctrl:1
	v_pk_fma_f32 v[12:13], v[54:55], v[20:21], v[12:13]
	ds_read_b128 v[36:39], v26 offset:7936
	v_pk_fma_f32 v[12:13], v[56:57], v[22:23], v[12:13]
	ds_read_b128 v[40:43], v26 offset:7952
	v_pk_fma_f32 v[12:13], v[58:59], v[24:25], v[12:13]
	ds_read_b128 v[52:55], v26 offset:8448
	v_add_f32_e32 v104, v12, v13
	ds_read_b128 v[56:59], v26 offset:8464
	v_add_f32_dpp v103, v103, v103 row_half_mirror row_mask:0xf bank_mask:0x5
	v_add_f32_dpp v100, v104, v104 row_half_mirror row_mask:0xf bank_mask:0xa
	ds_read_b128 v[64:67], v26 offset:8960
	ds_read_b128 v[68:71], v26 offset:8976
	s_waitcnt lgkmcnt(9)
	v_pk_fma_f32 v[18:19], v[72:73], v[10:11], v[116:117] op_sel_hi:[1,0,1]
	v_pk_fma_f32 v[20:21], v[74:75], v[10:11], v[118:119] op_sel_hi:[1,0,1]
	v_pk_mul_f32 v[8:9], v[18:19], v[28:29]
	v_pk_fma_f32 v[22:23], v[76:77], v[10:11], v[120:121] op_sel_hi:[1,0,1]
	v_pk_fma_f32 v[8:9], v[20:21], v[30:31], v[8:9]
	v_pk_fma_f32 v[24:25], v[78:79], v[10:11], v[122:123] op_sel_hi:[1,0,1]
	v_pk_fma_f32 v[8:9], v[22:23], v[32:33], v[8:9]
	ds_read_b128 v[80:83], v26 offset:9472
	v_pk_fma_f32 v[8:9], v[24:25], v[34:35], v[8:9]
	ds_read_b128 v[84:87], v26 offset:9488
	v_add_f32_e32 v8, v8, v9
	ds_read_b32 v96, v27 offset:9984
	s_waitcnt lgkmcnt(9)
	v_pk_fma_f32 v[116:117], v[60:61], v[44:45], v[18:19] op_sel_hi:[0,1,1]
	v_add_f32_dpp v8, v8, v8 quad_perm:[1,0,3,2] row_mask:0xf bank_mask:0xf bound_ctrl:1
	v_pk_fma_f32 v[118:119], v[60:61], v[46:47], v[20:21] op_sel_hi:[0,1,1]
	v_pk_fma_f32 v[120:121], v[60:61], v[48:49], v[22:23] op_sel_hi:[0,1,1]
	v_add_f32_dpp v8, v8, v8 quad_perm:[2,3,0,1] row_mask:0xf bank_mask:0xf bound_ctrl:1
	v_pk_fma_f32 v[122:123], v[60:61], v[50:51], v[24:25] op_sel_hi:[0,1,1]
	v_pk_mul_f32 v[14:15], v[88:89], v[18:19]
	v_add_f32_dpp v8, v8, v8 row_half_mirror row_mask:0xf bank_mask:0xf bound_ctrl:1
	v_pk_fma_f32 v[14:15], v[90:91], v[20:21], v[14:15]
	ds_read_b128 v[72:75], v26 offset:9216
	v_pk_fma_f32 v[14:15], v[92:93], v[22:23], v[14:15]
	ds_read_b128 v[76:79], v26 offset:9232
	v_pk_fma_f32 v[14:15], v[94:95], v[24:25], v[14:15]
	ds_read_b128 v[88:91], v26 offset:9728
	v_add_f32_e32 v105, v14, v15
	ds_read_b128 v[92:95], v26 offset:9744
	ds_read_b128 v[28:31], v26 offset:10240
	v_add_f32_dpp v101, v105, v105 row_half_mirror row_mask:0xf bank_mask:0xa
	ds_read_b128 v[32:35], v26 offset:10256
	s_waitcnt lgkmcnt(9)
	v_pk_fma_f32 v[18:19], v[36:37], v[8:9], v[116:117] op_sel_hi:[1,0,1]
	v_pk_fma_f32 v[20:21], v[38:39], v[8:9], v[118:119] op_sel_hi:[1,0,1]
	v_pk_mul_f32 v[10:11], v[18:19], v[64:65]
	v_pk_fma_f32 v[22:23], v[40:41], v[8:9], v[120:121] op_sel_hi:[1,0,1]
	v_pk_fma_f32 v[10:11], v[20:21], v[66:67], v[10:11]
	v_pk_fma_f32 v[24:25], v[42:43], v[8:9], v[122:123] op_sel_hi:[1,0,1]
	v_pk_fma_f32 v[10:11], v[22:23], v[68:69], v[10:11]
	ds_read_b128 v[44:47], v26 offset:10752
	v_pk_fma_f32 v[10:11], v[24:25], v[70:71], v[10:11]
	ds_read_b128 v[48:51], v26 offset:10768
	v_add_f32_e32 v10, v10, v11
	ds_read_b32 v60, v27 offset:11264
	s_waitcnt lgkmcnt(9)
	v_pk_fma_f32 v[116:117], v[96:97], v[80:81], v[18:19] op_sel_hi:[0,1,1]
	v_add_f32_dpp v10, v10, v10 quad_perm:[1,0,3,2] row_mask:0xf bank_mask:0xf bound_ctrl:1
	v_pk_fma_f32 v[118:119], v[96:97], v[82:83], v[20:21] op_sel_hi:[0,1,1]
	v_pk_fma_f32 v[120:121], v[96:97], v[84:85], v[22:23] op_sel_hi:[0,1,1]
	v_add_f32_dpp v10, v10, v10 quad_perm:[2,3,0,1] row_mask:0xf bank_mask:0xf bound_ctrl:1
	v_pk_fma_f32 v[122:123], v[96:97], v[86:87], v[24:25] op_sel_hi:[0,1,1]
	v_pk_mul_f32 v[12:13], v[52:53], v[18:19]
	v_add_f32_dpp v10, v10, v10 row_half_mirror row_mask:0xf bank_mask:0xf bound_ctrl:1
	v_pk_fma_f32 v[12:13], v[54:55], v[20:21], v[12:13]
	ds_read_b128 v[36:39], v26 offset:10496
	v_pk_fma_f32 v[12:13], v[56:57], v[22:23], v[12:13]
	ds_read_b128 v[40:43], v26 offset:10512
	v_pk_fma_f32 v[12:13], v[58:59], v[24:25], v[12:13]
	ds_read_b128 v[52:55], v26 offset:11008
	v_add_f32_e32 v106, v12, v13
	ds_read_b128 v[56:59], v26 offset:11024
	ds_read_b128 v[64:67], v26 offset:11520
	v_add_f32_dpp v102, v106, v106 row_half_mirror row_mask:0xf bank_mask:0xa
	ds_read_b128 v[68:71], v26 offset:11536
	s_waitcnt lgkmcnt(9)
	v_pk_fma_f32 v[18:19], v[72:73], v[10:11], v[116:117] op_sel_hi:[1,0,1]
	v_pk_fma_f32 v[20:21], v[74:75], v[10:11], v[118:119] op_sel_hi:[1,0,1]
	v_pk_fma_f32 v[22:23], v[76:77], v[10:11], v[120:121] op_sel_hi:[1,0,1]
	v_pk_fma_f32 v[24:25], v[78:79], v[10:11], v[122:123] op_sel_hi:[1,0,1]
	v_pk_mul_f32 v[108:109], v[124:125], v[18:19]
	v_pk_mul_f32 v[110:111], v[126:127], v[20:21]
	v_pk_mul_f32 v[8:9], v[108:109], v[28:29]
	v_pk_mul_f32 v[112:113], v[128:129], v[22:23]
	v_pk_fma_f32 v[8:9], v[110:111], v[30:31], v[8:9]
	v_pk_mul_f32 v[114:115], v[130:131], v[24:25]
	v_pk_fma_f32 v[8:9], v[112:113], v[32:33], v[8:9]
	ds_read_b128 v[80:83], v26 offset:12032
	v_pk_fma_f32 v[8:9], v[114:115], v[34:35], v[8:9]
	ds_read_b128 v[84:87], v26 offset:12048
	v_add_f32_e32 v8, v8, v9
	ds_read_b32 v96, v27 offset:12544
	s_waitcnt lgkmcnt(9)
; #define LAS __attribute__((address_space(3)))
; __device__ __forceinline__ float sum8(float x) { x += dppf<0xB1>(x); x += dppf<0x4E>(x); x += dppf<0x141>(x); return x; }
; __global__ void __launch_bounds__(512, 2) fwd_megakernel(Params P) {
;     ...
;                             for (int tt = 0; tt < 32; tt += 8) {
;                                 float yk = 0.f;
;                                 const f32x4 ge0 = *(const LAS f32x4*)(pk + 40960 + (tt >> 3) * 256), ge1 = *(const LAS f32x4*)(pk + 40960 + (tt >> 3) * 256 + 16);
; #pragma unroll
;                                 for (int j = 0; j < 8; ++j) {
;                                     if (j < 7 || tt + 8 < 32) SCAN_LOAD(rg2[(j + 1) & 1], rv2[(j + 1) & 1], tt + j + 1);
;                                     __builtin_amdgcn_sched_barrier(0);
;                                     const f32x4 (&cur)[8] = rg2[j & 1]; const float curv = rv2[j & 1];
;                                     const f32x2 v2 = {curv, curv};
;                                     const f32x2 pa = v2 * cur[4].xy + Sa, pb = v2 * cur[4].zw + Sb, pc = v2 * cur[5].xy + Sc, pd = v2 * cur[5].zw + Sd;
;                                     f32x2 t0 = Sa * cur[0].xy; t0 = Sb * cur[0].zw + t0;
;                                     f32x2 t1 = Sc * cur[1].xy; t1 = Sd * cur[1].zw + t1;
;                                     const f32x2 t = t0 + t1;
;                                     float sa = sum8(t.x + t.y);
;                                     const f32x2 sa2 = {sa, sa};
;                                     Sa = sa2 * cur[2].xy + pa; Sb = sa2 * cur[2].zw + pb; Sc = sa2 * cur[3].xy + pc; Sd = sa2 * cur[3].zw + pd;
;                                     f32x2 u0 = Sa * cur[6].xy; u0 = Sb * cur[6].zw + u0;
;                                     f32x2 u1 = Sc * cur[7].xy; u1 = Sd * cur[7].zw + u1;
;                                     const f32x2 u = u0 + u1;
;                                     const float y = sum8(u.x + u.y);
;                                     yk = (kq == j) ? y : yk;
;                                 }
;                                 Sa *= ge0.xy; Sb *= ge0.zw; Sc *= ge1.xy; Sd *= ge1.zw;
;                                 yout[(size_t)(c * 32 + tt + kq) * 1024] = (f16)yk;
	v_pk_fma_f32 v[116:117], v[60:61], v[44:45], v[108:109] op_sel_hi:[0,1,1]
	v_add_f32_dpp v8, v8, v8 quad_perm:[1,0,3,2] row_mask:0xf bank_mask:0xf bound_ctrl:1
	v_pk_fma_f32 v[118:119], v[60:61], v[46:47], v[110:111] op_sel_hi:[0,1,1]
	v_pk_fma_f32 v[120:121], v[60:61], v[48:49], v[112:113] op_sel_hi:[0,1,1]
	v_add_f32_dpp v8, v8, v8 quad_perm:[2,3,0,1] row_mask:0xf bank_mask:0xf bound_ctrl:1
	v_pk_fma_f32 v[122:123], v[60:61], v[50:51], v[114:115] op_sel_hi:[0,1,1]
	v_pk_mul_f32 v[14:15], v[88:89], v[18:19]
	v_add_f32_dpp v8, v8, v8 row_half_mirror row_mask:0xf bank_mask:0xf bound_ctrl:1
	v_pk_fma_f32 v[14:15], v[90:91], v[20:21], v[14:15]
	ds_read_b128 v[72:75], v26 offset:11776
	v_pk_fma_f32 v[14:15], v[92:93], v[22:23], v[14:15]
	ds_read_b128 v[76:79], v26 offset:11792
	v_pk_fma_f32 v[14:15], v[94:95], v[24:25], v[14:15]
	ds_read_b128 v[88:91], v26 offset:12288
	v_add_f32_e32 v107, v14, v15
	ds_read_b128 v[92:95], v26 offset:12304
	v_add_f32_dpp v16, v100, v100 quad_perm:[2,3,0,1] row_mask:0xf bank_mask:0xf bound_ctrl:1
	v_add_f32_dpp v103, v107, v107 row_half_mirror row_mask:0xf bank_mask:0xa
	v_add_f32_dpp v62, v101, v101 quad_perm:[2,3,0,1] row_mask:0xf bank_mask:0xf bound_ctrl:1
	v_add_f32_dpp v17, v102, v102 quad_perm:[2,3,0,1] row_mask:0xf bank_mask:0xf bound_ctrl:1
	v_add_f32_dpp v63, v103, v103 quad_perm:[2,3,0,1] row_mask:0xf bank_mask:0xf bound_ctrl:1
	v_cndmask_b32_e64 v61, v16, v17, s[100:101]
	v_cndmask_b32_e64 v97, v62, v63, s[100:101]
	ds_read_b128 v[28:31], v26 offset:12800
	v_add_f32_dpp v16, v61, v61 quad_perm:[1,0,3,2] row_mask:0xf bank_mask:0xf bound_ctrl:1
	v_add_f32_dpp v17, v97, v97 quad_perm:[1,0,3,2] row_mask:0xf bank_mask:0xf bound_ctrl:1
	ds_read_b128 v[32:35], v26 offset:12816
	v_cndmask_b32_e64 v16, v16, v17, s[44:45]
	s_waitcnt lgkmcnt(6)
	v_pk_fma_f32 v[108:109], v[36:37], v[8:9], v[116:117] op_sel_hi:[1,0,1]
	v_cvt_f16_f32_e32 v17, v16
	v_pk_fma_f32 v[110:111], v[38:39], v[8:9], v[118:119] op_sel_hi:[1,0,1]
	global_store_short v[98:99], v17, off
	v_pk_mul_f32 v[10:11], v[108:109], v[64:65]
	v_add_co_u32_e32 v98, vcc, 0x4000, v98
	v_pk_fma_f32 v[112:113], v[40:41], v[8:9], v[120:121] op_sel_hi:[1,0,1]
	v_pk_fma_f32 v[10:11], v[110:111], v[66:67], v[10:11]
	v_addc_co_u32_e32 v99, vcc, 0, v99, vcc
	v_pk_fma_f32 v[114:115], v[42:43], v[8:9], v[122:123] op_sel_hi:[1,0,1]
	v_pk_fma_f32 v[10:11], v[112:113], v[68:69], v[10:11]
	ds_read_b128 v[44:47], v26 offset:13312
	v_pk_fma_f32 v[10:11], v[114:115], v[70:71], v[10:11]
	ds_read_b128 v[48:51], v26 offset:13328
	v_add_f32_e32 v10, v10, v11
	ds_read_b32 v60, v27 offset:13824
	v_pk_fma_f32 v[116:117], v[96:97], v[80:81], v[108:109] op_sel_hi:[0,1,1]
	v_add_f32_dpp v10, v10, v10 quad_perm:[1,0,3,2] row_mask:0xf bank_mask:0xf bound_ctrl:1
	v_pk_fma_f32 v[118:119], v[96:97], v[82:83], v[110:111] op_sel_hi:[0,1,1]
	v_pk_fma_f32 v[120:121], v[96:97], v[84:85], v[112:113] op_sel_hi:[0,1,1]
	v_add_f32_dpp v10, v10, v10 quad_perm:[2,3,0,1] row_mask:0xf bank_mask:0xf bound_ctrl:1
	v_pk_fma_f32 v[122:123], v[96:97], v[86:87], v[114:115] op_sel_hi:[0,1,1]
	v_pk_mul_f32 v[12:13], v[52:53], v[108:109]
	v_add_f32_dpp v10, v10, v10 row_half_mirror row_mask:0xf bank_mask:0xf bound_ctrl:1
	v_pk_fma_f32 v[12:13], v[54:55], v[110:111], v[12:13]
	ds_read_b128 v[36:39], v26 offset:13056
	v_pk_fma_f32 v[12:13], v[56:57], v[112:113], v[12:13]
	ds_read_b128 v[40:43], v26 offset:13072
	v_pk_fma_f32 v[12:13], v[58:59], v[114:115], v[12:13]
	ds_read_b128 v[52:55], v26 offset:13568
	v_add_f32_e32 v100, v12, v13
	ds_read_b128 v[56:59], v26 offset:13584
	ds_read_b128 v[124:127], v26 offset:41216
	ds_read_b128 v[128:131], v26 offset:41232
	ds_read_b128 v[64:67], v26 offset:14080
	ds_read_b128 v[68:71], v26 offset:14096
	s_waitcnt lgkmcnt(11)
	v_pk_fma_f32 v[108:109], v[72:73], v[10:11], v[116:117] op_sel_hi:[1,0,1]
	v_pk_fma_f32 v[110:111], v[74:75], v[10:11], v[118:119] op_sel_hi:[1,0,1]
	v_pk_mul_f32 v[8:9], v[108:109], v[28:29]
	v_pk_fma_f32 v[112:113], v[76:77], v[10:11], v[120:121] op_sel_hi:[1,0,1]
	v_pk_fma_f32 v[8:9], v[110:111], v[30:31], v[8:9]
	v_pk_fma_f32 v[114:115], v[78:79], v[10:11], v[122:123] op_sel_hi:[1,0,1]
	v_pk_fma_f32 v[8:9], v[112:113], v[32:33], v[8:9]
	ds_read_b128 v[80:83], v26 offset:14592
	v_pk_fma_f32 v[8:9], v[114:115], v[34:35], v[8:9]
	ds_read_b128 v[84:87], v26 offset:14608
	v_add_f32_e32 v8, v8, v9
	ds_read_b32 v96, v27 offset:15104
	s_waitcnt lgkmcnt(11)
	v_pk_fma_f32 v[116:117], v[60:61], v[44:45], v[108:109] op_sel_hi:[0,1,1]
	v_add_f32_dpp v8, v8, v8 quad_perm:[1,0,3,2] row_mask:0xf bank_mask:0xf bound_ctrl:1
	v_pk_fma_f32 v[118:119], v[60:61], v[46:47], v[110:111] op_sel_hi:[0,1,1]
	v_pk_fma_f32 v[120:121], v[60:61], v[48:49], v[112:113] op_sel_hi:[0,1,1]
	v_add_f32_dpp v8, v8, v8 quad_perm:[2,3,0,1] row_mask:0xf bank_mask:0xf bound_ctrl:1
	v_pk_fma_f32 v[122:123], v[60:61], v[50:51], v[114:115] op_sel_hi:[0,1,1]
	v_pk_mul_f32 v[14:15], v[88:89], v[108:109]
	v_add_f32_dpp v8, v8, v8 row_half_mirror row_mask:0xf bank_mask:0xf bound_ctrl:1
	v_pk_fma_f32 v[14:15], v[90:91], v[110:111], v[14:15]
	ds_read_b128 v[72:75], v26 offset:14336
	v_pk_fma_f32 v[14:15], v[92:93], v[112:113], v[14:15]
	ds_read_b128 v[76:79], v26 offset:14352
	v_pk_fma_f32 v[14:15], v[94:95], v[114:115], v[14:15]
	ds_read_b128 v[88:91], v26 offset:14848
	v_add_f32_e32 v101, v14, v15
	ds_read_b128 v[92:95], v26 offset:14864
	v_add_f32_dpp v100, v100, v100 row_half_mirror row_mask:0xf bank_mask:0x5
	ds_read_b128 v[28:31], v26 offset:15360
	ds_read_b128 v[32:35], v26 offset:15376
	s_waitcnt lgkmcnt(9)
; #define LAS __attribute__((address_space(3)))
; __device__ __forceinline__ float sum8(float x) { x += dppf<0xB1>(x); x += dppf<0x4E>(x); x += dppf<0x141>(x); return x; }
; __global__ void __launch_bounds__(512, 2) fwd_megakernel(Params P) {
;     ...
;                             for (int tt = 0; tt < 32; tt += 8) {
;                                 float yk = 0.f;
;                                 const f32x4 ge0 = *(const LAS f32x4*)(pk + 40960 + (tt >> 3) * 256), ge1 = *(const LAS f32x4*)(pk + 40960 + (tt >> 3) * 256 + 16);
; #pragma unroll
;                                 for (int j = 0; j < 8; ++j) {
;                                     if (j < 7 || tt + 8 < 32) SCAN_LOAD(rg2[(j + 1) & 1], rv2[(j + 1) & 1], tt + j + 1);
;                                     __builtin_amdgcn_sched_barrier(0);
;                                     const f32x4 (&cur)[8] = rg2[j & 1]; const float curv = rv2[j & 1];
;                                     const f32x2 v2 = {curv, curv};
;                                     const f32x2 pa = v2 * cur[4].xy + Sa, pb = v2 * cur[4].zw + Sb, pc = v2 * cur[5].xy + Sc, pd = v2 * cur[5].zw + Sd;
;                                     f32x2 t0 = Sa * cur[0].xy; t0 = Sb * cur[0].zw + t0;
;                                     f32x2 t1 = Sc * cur[1].xy; t1 = Sd * cur[1].zw + t1;
;                                     const f32x2 t = t0 + t1;
;                                     float sa = sum8(t.x + t.y);
;                                     const f32x2 sa2 = {sa, sa};
;                                     Sa = sa2 * cur[2].xy + pa; Sb = sa2 * cur[2].zw + pb; Sc = sa2 * cur[3].xy + pc; Sd = sa2 * cur[3].zw + pd;
;                                     f32x2 u0 = Sa * cur[6].xy; u0 = Sb * cur[6].zw + u0;
;                                     f32x2 u1 = Sc * cur[7].xy; u1 = Sd * cur[7].zw + u1;
;                                     const f32x2 u = u0 + u1;
;                                     const float y = sum8(u.x + u.y);
;                                     yk = (kq == j) ? y : yk;
;                                 }
;                                 Sa *= ge0.xy; Sb *= ge0.zw; Sc *= ge1.xy; Sd *= ge1.zw;
;                                 yout[(size_t)(c * 32 + tt + kq) * 1024] = (f16)yk;
	v_pk_fma_f32 v[108:109], v[36:37], v[8:9], v[116:117] op_sel_hi:[1,0,1]
	v_pk_fma_f32 v[110:111], v[38:39], v[8:9], v[118:119] op_sel_hi:[1,0,1]
	v_pk_mul_f32 v[10:11], v[108:109], v[64:65]
	v_pk_fma_f32 v[112:113], v[40:41], v[8:9], v[120:121] op_sel_hi:[1,0,1]
	v_pk_fma_f32 v[10:11], v[110:111], v[66:67], v[10:11]
	v_pk_fma_f32 v[114:115], v[42:43], v[8:9], v[122:123] op_sel_hi:[1,0,1]
	v_pk_fma_f32 v[10:11], v[112:113], v[68:69], v[10:11]
	ds_read_b128 v[44:47], v26 offset:15872
	v_pk_fma_f32 v[10:11], v[114:115], v[70:71], v[10:11]
	ds_read_b128 v[48:51], v26 offset:15888
	v_add_f32_e32 v10, v10, v11
	ds_read_b32 v60, v27 offset:16384
	s_waitcnt lgkmcnt(9)
	v_pk_fma_f32 v[116:117], v[96:97], v[80:81], v[108:109] op_sel_hi:[0,1,1]
	v_add_f32_dpp v10, v10, v10 quad_perm:[1,0,3,2] row_mask:0xf bank_mask:0xf bound_ctrl:1
	v_pk_fma_f32 v[118:119], v[96:97], v[82:83], v[110:111] op_sel_hi:[0,1,1]
	v_pk_fma_f32 v[120:121], v[96:97], v[84:85], v[112:113] op_sel_hi:[0,1,1]
	v_add_f32_dpp v10, v10, v10 quad_perm:[2,3,0,1] row_mask:0xf bank_mask:0xf bound_ctrl:1
	v_pk_fma_f32 v[122:123], v[96:97], v[86:87], v[114:115] op_sel_hi:[0,1,1]
	v_pk_mul_f32 v[12:13], v[52:53], v[108:109]
	v_add_f32_dpp v10, v10, v10 row_half_mirror row_mask:0xf bank_mask:0xf bound_ctrl:1
	v_pk_fma_f32 v[12:13], v[54:55], v[110:111], v[12:13]
	ds_read_b128 v[36:39], v26 offset:15616
	v_pk_fma_f32 v[12:13], v[56:57], v[112:113], v[12:13]
	ds_read_b128 v[40:43], v26 offset:15632
	v_pk_fma_f32 v[12:13], v[58:59], v[114:115], v[12:13]
	ds_read_b128 v[52:55], v26 offset:16128
	v_add_f32_e32 v102, v12, v13
	ds_read_b128 v[56:59], v26 offset:16144
	v_add_f32_dpp v101, v101, v101 row_half_mirror row_mask:0xf bank_mask:0x5
	ds_read_b128 v[64:67], v26 offset:16640
	ds_read_b128 v[68:71], v26 offset:16656
	s_waitcnt lgkmcnt(9)
	v_pk_fma_f32 v[108:109], v[72:73], v[10:11], v[116:117] op_sel_hi:[1,0,1]
	v_pk_fma_f32 v[110:111], v[74:75], v[10:11], v[118:119] op_sel_hi:[1,0,1]
	v_pk_mul_f32 v[8:9], v[108:109], v[28:29]
	v_pk_fma_f32 v[112:113], v[76:77], v[10:11], v[120:121] op_sel_hi:[1,0,1]
	v_pk_fma_f32 v[8:9], v[110:111], v[30:31], v[8:9]
	v_pk_fma_f32 v[114:115], v[78:79], v[10:11], v[122:123] op_sel_hi:[1,0,1]
	v_pk_fma_f32 v[8:9], v[112:113], v[32:33], v[8:9]
	ds_read_b128 v[80:83], v26 offset:17152
	v_pk_fma_f32 v[8:9], v[114:115], v[34:35], v[8:9]
	ds_read_b128 v[84:87], v26 offset:17168
	v_add_f32_e32 v8, v8, v9
	ds_read_b32 v96, v27 offset:17664
	s_waitcnt lgkmcnt(9)
	v_pk_fma_f32 v[116:117], v[60:61], v[44:45], v[108:109] op_sel_hi:[0,1,1]
	v_add_f32_dpp v8, v8, v8 quad_perm:[1,0,3,2] row_mask:0xf bank_mask:0xf bound_ctrl:1
	v_pk_fma_f32 v[118:119], v[60:61], v[46:47], v[110:111] op_sel_hi:[0,1,1]
	v_pk_fma_f32 v[120:121], v[60:61], v[48:49], v[112:113] op_sel_hi:[0,1,1]
	v_add_f32_dpp v8, v8, v8 quad_perm:[2,3,0,1] row_mask:0xf bank_mask:0xf bound_ctrl:1
	v_pk_fma_f32 v[122:123], v[60:61], v[50:51], v[114:115] op_sel_hi:[0,1,1]
	v_pk_mul_f32 v[14:15], v[88:89], v[108:109]
	v_add_f32_dpp v8, v8, v8 row_half_mirror row_mask:0xf bank_mask:0xf bound_ctrl:1
	v_pk_fma_f32 v[14:15], v[90:91], v[110:111], v[14:15]
	ds_read_b128 v[72:75], v26 offset:16896
	v_pk_fma_f32 v[14:15], v[92:93], v[112:113], v[14:15]
	ds_read_b128 v[76:79], v26 offset:16912
	v_pk_fma_f32 v[14:15], v[94:95], v[114:115], v[14:15]
	ds_read_b128 v[88:91], v26 offset:17408
	v_add_f32_e32 v103, v14, v15
	ds_read_b128 v[92:95], v26 offset:17424
	v_add_f32_dpp v102, v102, v102 row_half_mirror row_mask:0xf bank_mask:0x5
	ds_read_b128 v[28:31], v26 offset:17920
	ds_read_b128 v[32:35], v26 offset:17936
	s_waitcnt lgkmcnt(9)
	v_pk_fma_f32 v[108:109], v[36:37], v[8:9], v[116:117] op_sel_hi:[1,0,1]
	v_pk_fma_f32 v[110:111], v[38:39], v[8:9], v[118:119] op_sel_hi:[1,0,1]
	v_pk_mul_f32 v[10:11], v[108:109], v[64:65]
	v_pk_fma_f32 v[112:113], v[40:41], v[8:9], v[120:121] op_sel_hi:[1,0,1]
	v_pk_fma_f32 v[10:11], v[110:111], v[66:67], v[10:11]
	v_pk_fma_f32 v[114:115], v[42:43], v[8:9], v[122:123] op_sel_hi:[1,0,1]
	v_pk_fma_f32 v[10:11], v[112:113], v[68:69], v[10:11]
	ds_read_b128 v[44:47], v26 offset:18432
	v_pk_fma_f32 v[10:11], v[114:115], v[70:71], v[10:11]
	ds_read_b128 v[48:51], v26 offset:18448
	v_add_f32_e32 v10, v10, v11
	ds_read_b32 v60, v27 offset:18944
	s_waitcnt lgkmcnt(9)
	v_pk_fma_f32 v[116:117], v[96:97], v[80:81], v[108:109] op_sel_hi:[0,1,1]
	v_add_f32_dpp v10, v10, v10 quad_perm:[1,0,3,2] row_mask:0xf bank_mask:0xf bound_ctrl:1
	v_pk_fma_f32 v[118:119], v[96:97], v[82:83], v[110:111] op_sel_hi:[0,1,1]
	v_pk_fma_f32 v[120:121], v[96:97], v[84:85], v[112:113] op_sel_hi:[0,1,1]
	v_add_f32_dpp v10, v10, v10 quad_perm:[2,3,0,1] row_mask:0xf bank_mask:0xf bound_ctrl:1
	v_pk_fma_f32 v[122:123], v[96:97], v[86:87], v[114:115] op_sel_hi:[0,1,1]
	v_pk_mul_f32 v[12:13], v[52:53], v[108:109]
	v_add_f32_dpp v10, v10, v10 row_half_mirror row_mask:0xf bank_mask:0xf bound_ctrl:1
	v_pk_fma_f32 v[12:13], v[54:55], v[110:111], v[12:13]
	ds_read_b128 v[36:39], v26 offset:18176
	v_pk_fma_f32 v[12:13], v[56:57], v[112:113], v[12:13]
	ds_read_b128 v[40:43], v26 offset:18192
	v_pk_fma_f32 v[12:13], v[58:59], v[114:115], v[12:13]
	ds_read_b128 v[52:55], v26 offset:18688
	v_add_f32_e32 v104, v12, v13
	ds_read_b128 v[56:59], v26 offset:18704
	v_add_f32_dpp v103, v103, v103 row_half_mirror row_mask:0xf bank_mask:0x5
	v_add_f32_dpp v100, v104, v104 row_half_mirror row_mask:0xf bank_mask:0xa
	ds_read_b128 v[64:67], v26 offset:19200
	ds_read_b128 v[68:71], v26 offset:19216
	s_waitcnt lgkmcnt(9)
; #define LAS __attribute__((address_space(3)))
; __device__ __forceinline__ float sum8(float x) { x += dppf<0xB1>(x); x += dppf<0x4E>(x); x += dppf<0x141>(x); return x; }
; __global__ void __launch_bounds__(512, 2) fwd_megakernel(Params P) {
;     ...
;                             for (int tt = 0; tt < 32; tt += 8) {
;                                 float yk = 0.f;
;                                 const f32x4 ge0 = *(const LAS f32x4*)(pk + 40960 + (tt >> 3) * 256), ge1 = *(const LAS f32x4*)(pk + 40960 + (tt >> 3) * 256 + 16);
; #pragma unroll
;                                 for (int j = 0; j < 8; ++j) {
;                                     if (j < 7 || tt + 8 < 32) SCAN_LOAD(rg2[(j + 1) & 1], rv2[(j + 1) & 1], tt + j + 1);
;                                     __builtin_amdgcn_sched_barrier(0);
;                                     const f32x4 (&cur)[8] = rg2[j & 1]; const float curv = rv2[j & 1];
;                                     const f32x2 v2 = {curv, curv};
;                                     const f32x2 pa = v2 * cur[4].xy + Sa, pb = v2 * cur[4].zw + Sb, pc = v2 * cur[5].xy + Sc, pd = v2 * cur[5].zw + Sd;
;                                     f32x2 t0 = Sa * cur[0].xy; t0 = Sb * cur[0].zw + t0;
;                                     f32x2 t1 = Sc * cur[1].xy; t1 = Sd * cur[1].zw + t1;
;                                     const f32x2 t = t0 + t1;
;                                     float sa = sum8(t.x + t.y);
;                                     const f32x2 sa2 = {sa, sa};
;                                     Sa = sa2 * cur[2].xy + pa; Sb = sa2 * cur[2].zw + pb; Sc = sa2 * cur[3].xy + pc; Sd = sa2 * cur[3].zw + pd;
;                                     f32x2 u0 = Sa * cur[6].xy; u0 = Sb * cur[6].zw + u0;
;                                     f32x2 u1 = Sc * cur[7].xy; u1 = Sd * cur[7].zw + u1;
;                                     const f32x2 u = u0 + u1;
;                                     const float y = sum8(u.x + u.y);
;                                     yk = (kq == j) ? y : yk;
;                                 }
;                                 Sa *= ge0.xy; Sb *= ge0.zw; Sc *= ge1.xy; Sd *= ge1.zw;
;                                 yout[(size_t)(c * 32 + tt + kq) * 1024] = (f16)yk;
	v_pk_fma_f32 v[108:109], v[72:73], v[10:11], v[116:117] op_sel_hi:[1,0,1]
	v_pk_fma_f32 v[110:111], v[74:75], v[10:11], v[118:119] op_sel_hi:[1,0,1]
	v_pk_mul_f32 v[8:9], v[108:109], v[28:29]
	v_pk_fma_f32 v[112:113], v[76:77], v[10:11], v[120:121] op_sel_hi:[1,0,1]
	v_pk_fma_f32 v[8:9], v[110:111], v[30:31], v[8:9]
	v_pk_fma_f32 v[114:115], v[78:79], v[10:11], v[122:123] op_sel_hi:[1,0,1]
	v_pk_fma_f32 v[8:9], v[112:113], v[32:33], v[8:9]
	ds_read_b128 v[80:83], v26 offset:19712
	v_pk_fma_f32 v[8:9], v[114:115], v[34:35], v[8:9]
	ds_read_b128 v[84:87], v26 offset:19728
	v_add_f32_e32 v8, v8, v9
	ds_read_b32 v96, v27 offset:20224
	s_waitcnt lgkmcnt(9)
	v_pk_fma_f32 v[116:117], v[60:61], v[44:45], v[108:109] op_sel_hi:[0,1,1]
	v_add_f32_dpp v8, v8, v8 quad_perm:[1,0,3,2] row_mask:0xf bank_mask:0xf bound_ctrl:1
	v_pk_fma_f32 v[118:119], v[60:61], v[46:47], v[110:111] op_sel_hi:[0,1,1]
	v_pk_fma_f32 v[120:121], v[60:61], v[48:49], v[112:113] op_sel_hi:[0,1,1]
	v_add_f32_dpp v8, v8, v8 quad_perm:[2,3,0,1] row_mask:0xf bank_mask:0xf bound_ctrl:1
	v_pk_fma_f32 v[122:123], v[60:61], v[50:51], v[114:115] op_sel_hi:[0,1,1]
	v_pk_mul_f32 v[14:15], v[88:89], v[108:109]
	v_add_f32_dpp v8, v8, v8 row_half_mirror row_mask:0xf bank_mask:0xf bound_ctrl:1
	v_pk_fma_f32 v[14:15], v[90:91], v[110:111], v[14:15]
	ds_read_b128 v[72:75], v26 offset:19456
	v_pk_fma_f32 v[14:15], v[92:93], v[112:113], v[14:15]
	ds_read_b128 v[76:79], v26 offset:19472
	v_pk_fma_f32 v[14:15], v[94:95], v[114:115], v[14:15]
	ds_read_b128 v[88:91], v26 offset:19968
	v_add_f32_e32 v105, v14, v15
	ds_read_b128 v[92:95], v26 offset:19984
	ds_read_b128 v[28:31], v26 offset:20480
	v_add_f32_dpp v101, v105, v105 row_half_mirror row_mask:0xf bank_mask:0xa
	ds_read_b128 v[32:35], v26 offset:20496
	s_waitcnt lgkmcnt(9)
	v_pk_fma_f32 v[108:109], v[36:37], v[8:9], v[116:117] op_sel_hi:[1,0,1]
	v_pk_fma_f32 v[110:111], v[38:39], v[8:9], v[118:119] op_sel_hi:[1,0,1]
	v_pk_mul_f32 v[10:11], v[108:109], v[64:65]
	v_pk_fma_f32 v[112:113], v[40:41], v[8:9], v[120:121] op_sel_hi:[1,0,1]
	v_pk_fma_f32 v[10:11], v[110:111], v[66:67], v[10:11]
	v_pk_fma_f32 v[114:115], v[42:43], v[8:9], v[122:123] op_sel_hi:[1,0,1]
	v_pk_fma_f32 v[10:11], v[112:113], v[68:69], v[10:11]
	ds_read_b128 v[44:47], v26 offset:20992
	v_pk_fma_f32 v[10:11], v[114:115], v[70:71], v[10:11]
	ds_read_b128 v[48:51], v26 offset:21008
	v_add_f32_e32 v10, v10, v11
	ds_read_b32 v60, v27 offset:21504
	s_waitcnt lgkmcnt(9)
	v_pk_fma_f32 v[116:117], v[96:97], v[80:81], v[108:109] op_sel_hi:[0,1,1]
	v_add_f32_dpp v10, v10, v10 quad_perm:[1,0,3,2] row_mask:0xf bank_mask:0xf bound_ctrl:1
	v_pk_fma_f32 v[118:119], v[96:97], v[82:83], v[110:111] op_sel_hi:[0,1,1]
	v_pk_fma_f32 v[120:121], v[96:97], v[84:85], v[112:113] op_sel_hi:[0,1,1]
	v_add_f32_dpp v10, v10, v10 quad_perm:[2,3,0,1] row_mask:0xf bank_mask:0xf bound_ctrl:1
	v_pk_fma_f32 v[122:123], v[96:97], v[86:87], v[114:115] op_sel_hi:[0,1,1]
	v_pk_mul_f32 v[12:13], v[52:53], v[108:109]
	v_add_f32_dpp v10, v10, v10 row_half_mirror row_mask:0xf bank_mask:0xf bound_ctrl:1
	v_pk_fma_f32 v[12:13], v[54:55], v[110:111], v[12:13]
	ds_read_b128 v[36:39], v26 offset:20736
	v_pk_fma_f32 v[12:13], v[56:57], v[112:113], v[12:13]
	ds_read_b128 v[40:43], v26 offset:20752
	v_pk_fma_f32 v[12:13], v[58:59], v[114:115], v[12:13]
	ds_read_b128 v[52:55], v26 offset:21248
	v_add_f32_e32 v106, v12, v13
	ds_read_b128 v[56:59], v26 offset:21264
	ds_read_b128 v[64:67], v26 offset:21760
	v_add_f32_dpp v102, v106, v106 row_half_mirror row_mask:0xf bank_mask:0xa
	ds_read_b128 v[68:71], v26 offset:21776
	s_waitcnt lgkmcnt(9)
	v_pk_fma_f32 v[108:109], v[72:73], v[10:11], v[116:117] op_sel_hi:[1,0,1]
	v_pk_fma_f32 v[110:111], v[74:75], v[10:11], v[118:119] op_sel_hi:[1,0,1]
	v_pk_fma_f32 v[112:113], v[76:77], v[10:11], v[120:121] op_sel_hi:[1,0,1]
	v_pk_fma_f32 v[114:115], v[78:79], v[10:11], v[122:123] op_sel_hi:[1,0,1]
	v_pk_mul_f32 v[18:19], v[124:125], v[108:109]
	v_pk_mul_f32 v[20:21], v[126:127], v[110:111]
	v_pk_mul_f32 v[8:9], v[18:19], v[28:29]
	v_pk_mul_f32 v[22:23], v[128:129], v[112:113]
	v_pk_fma_f32 v[8:9], v[20:21], v[30:31], v[8:9]
	v_pk_mul_f32 v[24:25], v[130:131], v[114:115]
	v_pk_fma_f32 v[8:9], v[22:23], v[32:33], v[8:9]
	ds_read_b128 v[80:83], v26 offset:22272
	v_pk_fma_f32 v[8:9], v[24:25], v[34:35], v[8:9]
	ds_read_b128 v[84:87], v26 offset:22288
	v_add_f32_e32 v8, v8, v9
	ds_read_b32 v96, v27 offset:22784
	s_waitcnt lgkmcnt(9)
	v_pk_fma_f32 v[116:117], v[60:61], v[44:45], v[18:19] op_sel_hi:[0,1,1]
	v_add_f32_dpp v8, v8, v8 quad_perm:[1,0,3,2] row_mask:0xf bank_mask:0xf bound_ctrl:1
	v_pk_fma_f32 v[118:119], v[60:61], v[46:47], v[20:21] op_sel_hi:[0,1,1]
	v_pk_fma_f32 v[120:121], v[60:61], v[48:49], v[22:23] op_sel_hi:[0,1,1]
	v_add_f32_dpp v8, v8, v8 quad_perm:[2,3,0,1] row_mask:0xf bank_mask:0xf bound_ctrl:1
	v_pk_fma_f32 v[122:123], v[60:61], v[50:51], v[24:25] op_sel_hi:[0,1,1]
	v_pk_mul_f32 v[14:15], v[88:89], v[108:109]
	v_add_f32_dpp v8, v8, v8 row_half_mirror row_mask:0xf bank_mask:0xf bound_ctrl:1
	v_pk_fma_f32 v[14:15], v[90:91], v[110:111], v[14:15]
	ds_read_b128 v[72:75], v26 offset:22016
	v_pk_fma_f32 v[14:15], v[92:93], v[112:113], v[14:15]
	ds_read_b128 v[76:79], v26 offset:22032
	v_pk_fma_f32 v[14:15], v[94:95], v[114:115], v[14:15]
	ds_read_b128 v[88:91], v26 offset:22528
	v_add_f32_e32 v107, v14, v15
	ds_read_b128 v[92:95], v26 offset:22544
	v_add_f32_dpp v16, v100, v100 quad_perm:[2,3,0,1] row_mask:0xf bank_mask:0xf bound_ctrl:1
	v_add_f32_dpp v103, v107, v107 row_half_mirror row_mask:0xf bank_mask:0xa
	v_add_f32_dpp v62, v101, v101 quad_perm:[2,3,0,1] row_mask:0xf bank_mask:0xf bound_ctrl:1
	v_add_f32_dpp v17, v102, v102 quad_perm:[2,3,0,1] row_mask:0xf bank_mask:0xf bound_ctrl:1
	v_add_f32_dpp v63, v103, v103 quad_perm:[2,3,0,1] row_mask:0xf bank_mask:0xf bound_ctrl:1
	v_cndmask_b32_e64 v61, v16, v17, s[100:101]
	v_cndmask_b32_e64 v97, v62, v63, s[100:101]
	ds_read_b128 v[28:31], v26 offset:23040
	v_add_f32_dpp v16, v61, v61 quad_perm:[1,0,3,2] row_mask:0xf bank_mask:0xf bound_ctrl:1
	v_add_f32_dpp v17, v97, v97 quad_perm:[1,0,3,2] row_mask:0xf bank_mask:0xf bound_ctrl:1
	ds_read_b128 v[32:35], v26 offset:23056
	v_cndmask_b32_e64 v16, v16, v17, s[44:45]
	s_waitcnt lgkmcnt(6)
; #define LAS __attribute__((address_space(3)))
; __device__ __forceinline__ float sum8(float x) { x += dppf<0xB1>(x); x += dppf<0x4E>(x); x += dppf<0x141>(x); return x; }
; __global__ void __launch_bounds__(512, 2) fwd_megakernel(Params P) {
;     ...
;                             for (int tt = 0; tt < 32; tt += 8) {
;                                 float yk = 0.f;
;                                 const f32x4 ge0 = *(const LAS f32x4*)(pk + 40960 + (tt >> 3) * 256), ge1 = *(const LAS f32x4*)(pk + 40960 + (tt >> 3) * 256 + 16);
; #pragma unroll
;                                 for (int j = 0; j < 8; ++j) {
;                                     if (j < 7 || tt + 8 < 32) SCAN_LOAD(rg2[(j + 1) & 1], rv2[(j + 1) & 1], tt + j + 1);
;                                     __builtin_amdgcn_sched_barrier(0);
;                                     const f32x4 (&cur)[8] = rg2[j & 1]; const float curv = rv2[j & 1];
;                                     const f32x2 v2 = {curv, curv};
;                                     const f32x2 pa = v2 * cur[4].xy + Sa, pb = v2 * cur[4].zw + Sb, pc = v2 * cur[5].xy + Sc, pd = v2 * cur[5].zw + Sd;
;                                     f32x2 t0 = Sa * cur[0].xy; t0 = Sb * cur[0].zw + t0;
;                                     f32x2 t1 = Sc * cur[1].xy; t1 = Sd * cur[1].zw + t1;
;                                     const f32x2 t = t0 + t1;
;                                     float sa = sum8(t.x + t.y);
;                                     const f32x2 sa2 = {sa, sa};
;                                     Sa = sa2 * cur[2].xy + pa; Sb = sa2 * cur[2].zw + pb; Sc = sa2 * cur[3].xy + pc; Sd = sa2 * cur[3].zw + pd;
;                                     f32x2 u0 = Sa * cur[6].xy; u0 = Sb * cur[6].zw + u0;
;                                     f32x2 u1 = Sc * cur[7].xy; u1 = Sd * cur[7].zw + u1;
;                                     const f32x2 u = u0 + u1;
;                                     const float y = sum8(u.x + u.y);
;                                     yk = (kq == j) ? y : yk;
;                                 }
;                                 Sa *= ge0.xy; Sb *= ge0.zw; Sc *= ge1.xy; Sd *= ge1.zw;
;                                 yout[(size_t)(c * 32 + tt + kq) * 1024] = (f16)yk;
	v_pk_fma_f32 v[18:19], v[36:37], v[8:9], v[116:117] op_sel_hi:[1,0,1]
	v_cvt_f16_f32_e32 v17, v16
	v_pk_fma_f32 v[20:21], v[38:39], v[8:9], v[118:119] op_sel_hi:[1,0,1]
	global_store_short v[98:99], v17, off
	v_pk_mul_f32 v[10:11], v[18:19], v[64:65]
	v_add_co_u32_e32 v98, vcc, 0x4000, v98
	v_pk_fma_f32 v[22:23], v[40:41], v[8:9], v[120:121] op_sel_hi:[1,0,1]
	v_pk_fma_f32 v[10:11], v[20:21], v[66:67], v[10:11]
	v_addc_co_u32_e32 v99, vcc, 0, v99, vcc
	v_pk_fma_f32 v[24:25], v[42:43], v[8:9], v[122:123] op_sel_hi:[1,0,1]
	v_pk_fma_f32 v[10:11], v[22:23], v[68:69], v[10:11]
	ds_read_b128 v[44:47], v26 offset:23552
	v_pk_fma_f32 v[10:11], v[24:25], v[70:71], v[10:11]
	ds_read_b128 v[48:51], v26 offset:23568
	v_add_f32_e32 v10, v10, v11
	ds_read_b32 v60, v27 offset:24064
	v_pk_fma_f32 v[116:117], v[96:97], v[80:81], v[18:19] op_sel_hi:[0,1,1]
	v_add_f32_dpp v10, v10, v10 quad_perm:[1,0,3,2] row_mask:0xf bank_mask:0xf bound_ctrl:1
	v_pk_fma_f32 v[118:119], v[96:97], v[82:83], v[20:21] op_sel_hi:[0,1,1]
	v_pk_fma_f32 v[120:121], v[96:97], v[84:85], v[22:23] op_sel_hi:[0,1,1]
	v_add_f32_dpp v10, v10, v10 quad_perm:[2,3,0,1] row_mask:0xf bank_mask:0xf bound_ctrl:1
	v_pk_fma_f32 v[122:123], v[96:97], v[86:87], v[24:25] op_sel_hi:[0,1,1]
	v_pk_mul_f32 v[12:13], v[52:53], v[18:19]
	v_add_f32_dpp v10, v10, v10 row_half_mirror row_mask:0xf bank_mask:0xf bound_ctrl:1
	v_pk_fma_f32 v[12:13], v[54:55], v[20:21], v[12:13]
	ds_read_b128 v[36:39], v26 offset:23296
	v_pk_fma_f32 v[12:13], v[56:57], v[22:23], v[12:13]
	ds_read_b128 v[40:43], v26 offset:23312
	v_pk_fma_f32 v[12:13], v[58:59], v[24:25], v[12:13]
	ds_read_b128 v[52:55], v26 offset:23808
	v_add_f32_e32 v100, v12, v13
	ds_read_b128 v[56:59], v26 offset:23824
	ds_read_b128 v[124:127], v26 offset:41472
	ds_read_b128 v[128:131], v26 offset:41488
	ds_read_b128 v[64:67], v26 offset:24320
	ds_read_b128 v[68:71], v26 offset:24336
	s_waitcnt lgkmcnt(11)
	v_pk_fma_f32 v[18:19], v[72:73], v[10:11], v[116:117] op_sel_hi:[1,0,1]
	v_pk_fma_f32 v[20:21], v[74:75], v[10:11], v[118:119] op_sel_hi:[1,0,1]
	v_pk_mul_f32 v[8:9], v[18:19], v[28:29]
	v_pk_fma_f32 v[22:23], v[76:77], v[10:11], v[120:121] op_sel_hi:[1,0,1]
	v_pk_fma_f32 v[8:9], v[20:21], v[30:31], v[8:9]
	v_pk_fma_f32 v[24:25], v[78:79], v[10:11], v[122:123] op_sel_hi:[1,0,1]
	v_pk_fma_f32 v[8:9], v[22:23], v[32:33], v[8:9]
	ds_read_b128 v[80:83], v26 offset:24832
	v_pk_fma_f32 v[8:9], v[24:25], v[34:35], v[8:9]
	ds_read_b128 v[84:87], v26 offset:24848
	v_add_f32_e32 v8, v8, v9
	ds_read_b32 v96, v27 offset:25344
	s_waitcnt lgkmcnt(11)
	v_pk_fma_f32 v[116:117], v[60:61], v[44:45], v[18:19] op_sel_hi:[0,1,1]
	v_add_f32_dpp v8, v8, v8 quad_perm:[1,0,3,2] row_mask:0xf bank_mask:0xf bound_ctrl:1
	v_pk_fma_f32 v[118:119], v[60:61], v[46:47], v[20:21] op_sel_hi:[0,1,1]
	v_pk_fma_f32 v[120:121], v[60:61], v[48:49], v[22:23] op_sel_hi:[0,1,1]
	v_add_f32_dpp v8, v8, v8 quad_perm:[2,3,0,1] row_mask:0xf bank_mask:0xf bound_ctrl:1
	v_pk_fma_f32 v[122:123], v[60:61], v[50:51], v[24:25] op_sel_hi:[0,1,1]
	v_pk_mul_f32 v[14:15], v[88:89], v[18:19]
	v_add_f32_dpp v8, v8, v8 row_half_mirror row_mask:0xf bank_mask:0xf bound_ctrl:1
	v_pk_fma_f32 v[14:15], v[90:91], v[20:21], v[14:15]
	ds_read_b128 v[72:75], v26 offset:24576
	v_pk_fma_f32 v[14:15], v[92:93], v[22:23], v[14:15]
	ds_read_b128 v[76:79], v26 offset:24592
	v_pk_fma_f32 v[14:15], v[94:95], v[24:25], v[14:15]
	ds_read_b128 v[88:91], v26 offset:25088
	v_add_f32_e32 v101, v14, v15
	ds_read_b128 v[92:95], v26 offset:25104
	v_add_f32_dpp v100, v100, v100 row_half_mirror row_mask:0xf bank_mask:0x5
	ds_read_b128 v[28:31], v26 offset:25600
	ds_read_b128 v[32:35], v26 offset:25616
	s_waitcnt lgkmcnt(9)
	v_pk_fma_f32 v[18:19], v[36:37], v[8:9], v[116:117] op_sel_hi:[1,0,1]
	v_pk_fma_f32 v[20:21], v[38:39], v[8:9], v[118:119] op_sel_hi:[1,0,1]
	v_pk_mul_f32 v[10:11], v[18:19], v[64:65]
	v_pk_fma_f32 v[22:23], v[40:41], v[8:9], v[120:121] op_sel_hi:[1,0,1]
	v_pk_fma_f32 v[10:11], v[20:21], v[66:67], v[10:11]
	v_pk_fma_f32 v[24:25], v[42:43], v[8:9], v[122:123] op_sel_hi:[1,0,1]
	v_pk_fma_f32 v[10:11], v[22:23], v[68:69], v[10:11]
	ds_read_b128 v[44:47], v26 offset:26112
	v_pk_fma_f32 v[10:11], v[24:25], v[70:71], v[10:11]
	ds_read_b128 v[48:51], v26 offset:26128
	v_add_f32_e32 v10, v10, v11
	ds_read_b32 v60, v27 offset:26624
	s_waitcnt lgkmcnt(9)
	v_pk_fma_f32 v[116:117], v[96:97], v[80:81], v[18:19] op_sel_hi:[0,1,1]
	v_add_f32_dpp v10, v10, v10 quad_perm:[1,0,3,2] row_mask:0xf bank_mask:0xf bound_ctrl:1
	v_pk_fma_f32 v[118:119], v[96:97], v[82:83], v[20:21] op_sel_hi:[0,1,1]
	v_pk_fma_f32 v[120:121], v[96:97], v[84:85], v[22:23] op_sel_hi:[0,1,1]
	v_add_f32_dpp v10, v10, v10 quad_perm:[2,3,0,1] row_mask:0xf bank_mask:0xf bound_ctrl:1
	v_pk_fma_f32 v[122:123], v[96:97], v[86:87], v[24:25] op_sel_hi:[0,1,1]
	v_pk_mul_f32 v[12:13], v[52:53], v[18:19]
	v_add_f32_dpp v10, v10, v10 row_half_mirror row_mask:0xf bank_mask:0xf bound_ctrl:1
	v_pk_fma_f32 v[12:13], v[54:55], v[20:21], v[12:13]
	ds_read_b128 v[36:39], v26 offset:25856
	v_pk_fma_f32 v[12:13], v[56:57], v[22:23], v[12:13]
	ds_read_b128 v[40:43], v26 offset:25872
	v_pk_fma_f32 v[12:13], v[58:59], v[24:25], v[12:13]
	ds_read_b128 v[52:55], v26 offset:26368
	v_add_f32_e32 v102, v12, v13
	ds_read_b128 v[56:59], v26 offset:26384
	v_add_f32_dpp v101, v101, v101 row_half_mirror row_mask:0xf bank_mask:0x5
	ds_read_b128 v[64:67], v26 offset:26880
	ds_read_b128 v[68:71], v26 offset:26896
	s_waitcnt lgkmcnt(9)
; __device__ __forceinline__ float sum8(float x) { x += dppf<0xB1>(x); x += dppf<0x4E>(x); x += dppf<0x141>(x); return x; }
; __global__ void __launch_bounds__(512, 2) fwd_megakernel(Params P) {
;     ...
;                                 for (int j = 0; j < 8; ++j) {
;                                     if (j < 7 || tt + 8 < 32) SCAN_LOAD(rg2[(j + 1) & 1], rv2[(j + 1) & 1], tt + j + 1);
;                                     __builtin_amdgcn_sched_barrier(0);
;                                     const f32x4 (&cur)[8] = rg2[j & 1]; const float curv = rv2[j & 1];
;                                     const f32x2 v2 = {curv, curv};
;                                     const f32x2 pa = v2 * cur[4].xy + Sa, pb = v2 * cur[4].zw + Sb, pc = v2 * cur[5].xy + Sc, pd = v2 * cur[5].zw + Sd;
;                                     f32x2 t0 = Sa * cur[0].xy; t0 = Sb * cur[0].zw + t0;
;                                     f32x2 t1 = Sc * cur[1].xy; t1 = Sd * cur[1].zw + t1;
;                                     const f32x2 t = t0 + t1;
;                                     float sa = sum8(t.x + t.y);
;                                     const f32x2 sa2 = {sa, sa};
;                                     Sa = sa2 * cur[2].xy + pa; Sb = sa2 * cur[2].zw + pb; Sc = sa2 * cur[3].xy + pc; Sd = sa2 * cur[3].zw + pd;
;                                     f32x2 u0 = Sa * cur[6].xy; u0 = Sb * cur[6].zw + u0;
;                                     f32x2 u1 = Sc * cur[7].xy; u1 = Sd * cur[7].zw + u1;
;                                     const f32x2 u = u0 + u1;
;                                     const float y = sum8(u.x + u.y);
;                                     yk = (kq == j) ? y : yk;
;                                 }
	v_pk_fma_f32 v[18:19], v[72:73], v[10:11], v[116:117] op_sel_hi:[1,0,1]
	v_pk_fma_f32 v[20:21], v[74:75], v[10:11], v[118:119] op_sel_hi:[1,0,1]
	v_pk_mul_f32 v[8:9], v[18:19], v[28:29]
	v_pk_fma_f32 v[22:23], v[76:77], v[10:11], v[120:121] op_sel_hi:[1,0,1]
	v_pk_fma_f32 v[8:9], v[20:21], v[30:31], v[8:9]
	v_pk_fma_f32 v[24:25], v[78:79], v[10:11], v[122:123] op_sel_hi:[1,0,1]
	v_pk_fma_f32 v[8:9], v[22:23], v[32:33], v[8:9]
	ds_read_b128 v[80:83], v26 offset:27392
	v_pk_fma_f32 v[8:9], v[24:25], v[34:35], v[8:9]
	ds_read_b128 v[84:87], v26 offset:27408
	v_add_f32_e32 v8, v8, v9
	ds_read_b32 v96, v27 offset:27904
	s_waitcnt lgkmcnt(9)
	v_pk_fma_f32 v[116:117], v[60:61], v[44:45], v[18:19] op_sel_hi:[0,1,1]
	v_add_f32_dpp v8, v8, v8 quad_perm:[1,0,3,2] row_mask:0xf bank_mask:0xf bound_ctrl:1
	v_pk_fma_f32 v[118:119], v[60:61], v[46:47], v[20:21] op_sel_hi:[0,1,1]
	v_pk_fma_f32 v[120:121], v[60:61], v[48:49], v[22:23] op_sel_hi:[0,1,1]
	v_add_f32_dpp v8, v8, v8 quad_perm:[2,3,0,1] row_mask:0xf bank_mask:0xf bound_ctrl:1
	v_pk_fma_f32 v[122:123], v[60:61], v[50:51], v[24:25] op_sel_hi:[0,1,1]
	v_pk_mul_f32 v[14:15], v[88:89], v[18:19]
	v_add_f32_dpp v8, v8, v8 row_half_mirror row_mask:0xf bank_mask:0xf bound_ctrl:1
	v_pk_fma_f32 v[14:15], v[90:91], v[20:21], v[14:15]
	ds_read_b128 v[72:75], v26 offset:27136
	v_pk_fma_f32 v[14:15], v[92:93], v[22:23], v[14:15]
	ds_read_b128 v[76:79], v26 offset:27152
	v_pk_fma_f32 v[14:15], v[94:95], v[24:25], v[14:15]
	ds_read_b128 v[88:91], v26 offset:27648
	v_add_f32_e32 v103, v14, v15
	ds_read_b128 v[92:95], v26 offset:27664
	v_add_f32_dpp v102, v102, v102 row_half_mirror row_mask:0xf bank_mask:0x5
	ds_read_b128 v[28:31], v26 offset:28160
	ds_read_b128 v[32:35], v26 offset:28176
	s_waitcnt lgkmcnt(9)
	v_pk_fma_f32 v[18:19], v[36:37], v[8:9], v[116:117] op_sel_hi:[1,0,1]
	v_pk_fma_f32 v[20:21], v[38:39], v[8:9], v[118:119] op_sel_hi:[1,0,1]
	v_pk_mul_f32 v[10:11], v[18:19], v[64:65]
	v_pk_fma_f32 v[22:23], v[40:41], v[8:9], v[120:121] op_sel_hi:[1,0,1]
	v_pk_fma_f32 v[10:11], v[20:21], v[66:67], v[10:11]
	v_pk_fma_f32 v[24:25], v[42:43], v[8:9], v[122:123] op_sel_hi:[1,0,1]
	v_pk_fma_f32 v[10:11], v[22:23], v[68:69], v[10:11]
	ds_read_b128 v[44:47], v26 offset:28672
	v_pk_fma_f32 v[10:11], v[24:25], v[70:71], v[10:11]
	ds_read_b128 v[48:51], v26 offset:28688
	v_add_f32_e32 v10, v10, v11
	ds_read_b32 v60, v27 offset:29184
	s_waitcnt lgkmcnt(9)
	v_pk_fma_f32 v[116:117], v[96:97], v[80:81], v[18:19] op_sel_hi:[0,1,1]
	v_add_f32_dpp v10, v10, v10 quad_perm:[1,0,3,2] row_mask:0xf bank_mask:0xf bound_ctrl:1
	v_pk_fma_f32 v[118:119], v[96:97], v[82:83], v[20:21] op_sel_hi:[0,1,1]
	v_pk_fma_f32 v[120:121], v[96:97], v[84:85], v[22:23] op_sel_hi:[0,1,1]
	v_add_f32_dpp v10, v10, v10 quad_perm:[2,3,0,1] row_mask:0xf bank_mask:0xf bound_ctrl:1
	v_pk_fma_f32 v[122:123], v[96:97], v[86:87], v[24:25] op_sel_hi:[0,1,1]
	v_pk_mul_f32 v[12:13], v[52:53], v[18:19]
	v_add_f32_dpp v10, v10, v10 row_half_mirror row_mask:0xf bank_mask:0xf bound_ctrl:1
	v_pk_fma_f32 v[12:13], v[54:55], v[20:21], v[12:13]
	ds_read_b128 v[36:39], v26 offset:28416
	v_pk_fma_f32 v[12:13], v[56:57], v[22:23], v[12:13]
	ds_read_b128 v[40:43], v26 offset:28432
	v_pk_fma_f32 v[12:13], v[58:59], v[24:25], v[12:13]
	ds_read_b128 v[52:55], v26 offset:28928
	v_add_f32_e32 v104, v12, v13
	ds_read_b128 v[56:59], v26 offset:28944
	v_add_f32_dpp v103, v103, v103 row_half_mirror row_mask:0xf bank_mask:0x5
	v_add_f32_dpp v100, v104, v104 row_half_mirror row_mask:0xf bank_mask:0xa
	ds_read_b128 v[64:67], v26 offset:29440
	ds_read_b128 v[68:71], v26 offset:29456
	s_waitcnt lgkmcnt(9)
	v_pk_fma_f32 v[18:19], v[72:73], v[10:11], v[116:117] op_sel_hi:[1,0,1]
	v_pk_fma_f32 v[20:21], v[74:75], v[10:11], v[118:119] op_sel_hi:[1,0,1]
	v_pk_mul_f32 v[8:9], v[18:19], v[28:29]
	v_pk_fma_f32 v[22:23], v[76:77], v[10:11], v[120:121] op_sel_hi:[1,0,1]
	v_pk_fma_f32 v[8:9], v[20:21], v[30:31], v[8:9]
	v_pk_fma_f32 v[24:25], v[78:79], v[10:11], v[122:123] op_sel_hi:[1,0,1]
	v_pk_fma_f32 v[8:9], v[22:23], v[32:33], v[8:9]
	ds_read_b128 v[80:83], v26 offset:29952
	v_pk_fma_f32 v[8:9], v[24:25], v[34:35], v[8:9]
	ds_read_b128 v[84:87], v26 offset:29968
	v_add_f32_e32 v8, v8, v9
	ds_read_b32 v96, v27 offset:30464
	s_waitcnt lgkmcnt(9)
	v_pk_fma_f32 v[116:117], v[60:61], v[44:45], v[18:19] op_sel_hi:[0,1,1]
	v_add_f32_dpp v8, v8, v8 quad_perm:[1,0,3,2] row_mask:0xf bank_mask:0xf bound_ctrl:1
	v_pk_fma_f32 v[118:119], v[60:61], v[46:47], v[20:21] op_sel_hi:[0,1,1]
	v_pk_fma_f32 v[120:121], v[60:61], v[48:49], v[22:23] op_sel_hi:[0,1,1]
	v_add_f32_dpp v8, v8, v8 quad_perm:[2,3,0,1] row_mask:0xf bank_mask:0xf bound_ctrl:1
	v_pk_fma_f32 v[122:123], v[60:61], v[50:51], v[24:25] op_sel_hi:[0,1,1]
	v_pk_mul_f32 v[14:15], v[88:89], v[18:19]
	v_add_f32_dpp v8, v8, v8 row_half_mirror row_mask:0xf bank_mask:0xf bound_ctrl:1
	v_pk_fma_f32 v[14:15], v[90:91], v[20:21], v[14:15]
	ds_read_b128 v[72:75], v26 offset:29696
	v_pk_fma_f32 v[14:15], v[92:93], v[22:23], v[14:15]
	ds_read_b128 v[76:79], v26 offset:29712
	v_pk_fma_f32 v[14:15], v[94:95], v[24:25], v[14:15]
	ds_read_b128 v[88:91], v26 offset:30208
	v_add_f32_e32 v105, v14, v15
	ds_read_b128 v[92:95], v26 offset:30224
	ds_read_b128 v[28:31], v26 offset:30720
	v_add_f32_dpp v101, v105, v105 row_half_mirror row_mask:0xf bank_mask:0xa
	ds_read_b128 v[32:35], v26 offset:30736
	s_waitcnt lgkmcnt(9)
; #define LAS __attribute__((address_space(3)))
; __device__ __forceinline__ float sum8(float x) { x += dppf<0xB1>(x); x += dppf<0x4E>(x); x += dppf<0x141>(x); return x; }
; __global__ void __launch_bounds__(512, 2) fwd_megakernel(Params P) {
;     ...
;                             for (int tt = 0; tt < 32; tt += 8) {
;                                 float yk = 0.f;
;                                 const f32x4 ge0 = *(const LAS f32x4*)(pk + 40960 + (tt >> 3) * 256), ge1 = *(const LAS f32x4*)(pk + 40960 + (tt >> 3) * 256 + 16);
; #pragma unroll
;                                 for (int j = 0; j < 8; ++j) {
;                                     if (j < 7 || tt + 8 < 32) SCAN_LOAD(rg2[(j + 1) & 1], rv2[(j + 1) & 1], tt + j + 1);
;                                     __builtin_amdgcn_sched_barrier(0);
;                                     const f32x4 (&cur)[8] = rg2[j & 1]; const float curv = rv2[j & 1];
;                                     const f32x2 v2 = {curv, curv};
;                                     const f32x2 pa = v2 * cur[4].xy + Sa, pb = v2 * cur[4].zw + Sb, pc = v2 * cur[5].xy + Sc, pd = v2 * cur[5].zw + Sd;
;                                     f32x2 t0 = Sa * cur[0].xy; t0 = Sb * cur[0].zw + t0;
;                                     f32x2 t1 = Sc * cur[1].xy; t1 = Sd * cur[1].zw + t1;
;                                     const f32x2 t = t0 + t1;
;                                     float sa = sum8(t.x + t.y);
;                                     const f32x2 sa2 = {sa, sa};
;                                     Sa = sa2 * cur[2].xy + pa; Sb = sa2 * cur[2].zw + pb; Sc = sa2 * cur[3].xy + pc; Sd = sa2 * cur[3].zw + pd;
;                                     f32x2 u0 = Sa * cur[6].xy; u0 = Sb * cur[6].zw + u0;
;                                     f32x2 u1 = Sc * cur[7].xy; u1 = Sd * cur[7].zw + u1;
;                                     const f32x2 u = u0 + u1;
;                                     const float y = sum8(u.x + u.y);
;                                     yk = (kq == j) ? y : yk;
;                                 }
;                                 Sa *= ge0.xy; Sb *= ge0.zw; Sc *= ge1.xy; Sd *= ge1.zw;
;                                 yout[(size_t)(c * 32 + tt + kq) * 1024] = (f16)yk;
	v_pk_fma_f32 v[18:19], v[36:37], v[8:9], v[116:117] op_sel_hi:[1,0,1]
	v_pk_fma_f32 v[20:21], v[38:39], v[8:9], v[118:119] op_sel_hi:[1,0,1]
	v_pk_mul_f32 v[10:11], v[18:19], v[64:65]
	v_pk_fma_f32 v[22:23], v[40:41], v[8:9], v[120:121] op_sel_hi:[1,0,1]
	v_pk_fma_f32 v[10:11], v[20:21], v[66:67], v[10:11]
	v_pk_fma_f32 v[24:25], v[42:43], v[8:9], v[122:123] op_sel_hi:[1,0,1]
	v_pk_fma_f32 v[10:11], v[22:23], v[68:69], v[10:11]
	ds_read_b128 v[44:47], v26 offset:31232
	v_pk_fma_f32 v[10:11], v[24:25], v[70:71], v[10:11]
	ds_read_b128 v[48:51], v26 offset:31248
	v_add_f32_e32 v10, v10, v11
	ds_read_b32 v60, v27 offset:31744
	s_waitcnt lgkmcnt(9)
	v_pk_fma_f32 v[116:117], v[96:97], v[80:81], v[18:19] op_sel_hi:[0,1,1]
	v_add_f32_dpp v10, v10, v10 quad_perm:[1,0,3,2] row_mask:0xf bank_mask:0xf bound_ctrl:1
	v_pk_fma_f32 v[118:119], v[96:97], v[82:83], v[20:21] op_sel_hi:[0,1,1]
	v_pk_fma_f32 v[120:121], v[96:97], v[84:85], v[22:23] op_sel_hi:[0,1,1]
	v_add_f32_dpp v10, v10, v10 quad_perm:[2,3,0,1] row_mask:0xf bank_mask:0xf bound_ctrl:1
	v_pk_fma_f32 v[122:123], v[96:97], v[86:87], v[24:25] op_sel_hi:[0,1,1]
	v_pk_mul_f32 v[12:13], v[52:53], v[18:19]
	v_add_f32_dpp v10, v10, v10 row_half_mirror row_mask:0xf bank_mask:0xf bound_ctrl:1
	v_pk_fma_f32 v[12:13], v[54:55], v[20:21], v[12:13]
	ds_read_b128 v[36:39], v26 offset:30976
	v_pk_fma_f32 v[12:13], v[56:57], v[22:23], v[12:13]
	ds_read_b128 v[40:43], v26 offset:30992
	v_pk_fma_f32 v[12:13], v[58:59], v[24:25], v[12:13]
	ds_read_b128 v[52:55], v26 offset:31488
	v_add_f32_e32 v106, v12, v13
	ds_read_b128 v[56:59], v26 offset:31504
	ds_read_b128 v[64:67], v26 offset:32000
	v_add_f32_dpp v102, v106, v106 row_half_mirror row_mask:0xf bank_mask:0xa
	ds_read_b128 v[68:71], v26 offset:32016
	s_waitcnt lgkmcnt(9)
	v_pk_fma_f32 v[18:19], v[72:73], v[10:11], v[116:117] op_sel_hi:[1,0,1]
	v_pk_fma_f32 v[20:21], v[74:75], v[10:11], v[118:119] op_sel_hi:[1,0,1]
	v_pk_fma_f32 v[22:23], v[76:77], v[10:11], v[120:121] op_sel_hi:[1,0,1]
	v_pk_fma_f32 v[24:25], v[78:79], v[10:11], v[122:123] op_sel_hi:[1,0,1]
	v_pk_mul_f32 v[108:109], v[124:125], v[18:19]
	v_pk_mul_f32 v[110:111], v[126:127], v[20:21]
	v_pk_mul_f32 v[8:9], v[108:109], v[28:29]
	v_pk_mul_f32 v[112:113], v[128:129], v[22:23]
	v_pk_fma_f32 v[8:9], v[110:111], v[30:31], v[8:9]
	v_pk_mul_f32 v[114:115], v[130:131], v[24:25]
	v_pk_fma_f32 v[8:9], v[112:113], v[32:33], v[8:9]
	ds_read_b128 v[80:83], v26 offset:32512
	v_pk_fma_f32 v[8:9], v[114:115], v[34:35], v[8:9]
	ds_read_b128 v[84:87], v26 offset:32528
	v_add_f32_e32 v8, v8, v9
	ds_read_b32 v96, v27 offset:33024
	s_waitcnt lgkmcnt(9)
	v_pk_fma_f32 v[116:117], v[60:61], v[44:45], v[108:109] op_sel_hi:[0,1,1]
	v_add_f32_dpp v8, v8, v8 quad_perm:[1,0,3,2] row_mask:0xf bank_mask:0xf bound_ctrl:1
	v_pk_fma_f32 v[118:119], v[60:61], v[46:47], v[110:111] op_sel_hi:[0,1,1]
	v_pk_fma_f32 v[120:121], v[60:61], v[48:49], v[112:113] op_sel_hi:[0,1,1]
	v_add_f32_dpp v8, v8, v8 quad_perm:[2,3,0,1] row_mask:0xf bank_mask:0xf bound_ctrl:1
	v_pk_fma_f32 v[122:123], v[60:61], v[50:51], v[114:115] op_sel_hi:[0,1,1]
	v_pk_mul_f32 v[14:15], v[88:89], v[18:19]
	v_add_f32_dpp v8, v8, v8 row_half_mirror row_mask:0xf bank_mask:0xf bound_ctrl:1
	v_pk_fma_f32 v[14:15], v[90:91], v[20:21], v[14:15]
	ds_read_b128 v[72:75], v26 offset:32256
	v_pk_fma_f32 v[14:15], v[92:93], v[22:23], v[14:15]
	ds_read_b128 v[76:79], v26 offset:32272
	v_pk_fma_f32 v[14:15], v[94:95], v[24:25], v[14:15]
	ds_read_b128 v[88:91], v26 offset:32768
	v_add_f32_e32 v107, v14, v15
	ds_read_b128 v[92:95], v26 offset:32784
	v_add_f32_dpp v16, v100, v100 quad_perm:[2,3,0,1] row_mask:0xf bank_mask:0xf bound_ctrl:1
	v_add_f32_dpp v103, v107, v107 row_half_mirror row_mask:0xf bank_mask:0xa
	v_add_f32_dpp v62, v101, v101 quad_perm:[2,3,0,1] row_mask:0xf bank_mask:0xf bound_ctrl:1
	v_add_f32_dpp v17, v102, v102 quad_perm:[2,3,0,1] row_mask:0xf bank_mask:0xf bound_ctrl:1
	v_add_f32_dpp v63, v103, v103 quad_perm:[2,3,0,1] row_mask:0xf bank_mask:0xf bound_ctrl:1
	v_cndmask_b32_e64 v61, v16, v17, s[100:101]
	v_cndmask_b32_e64 v97, v62, v63, s[100:101]
	ds_read_b128 v[28:31], v26 offset:33280
	v_add_f32_dpp v16, v61, v61 quad_perm:[1,0,3,2] row_mask:0xf bank_mask:0xf bound_ctrl:1
	v_add_f32_dpp v17, v97, v97 quad_perm:[1,0,3,2] row_mask:0xf bank_mask:0xf bound_ctrl:1
	ds_read_b128 v[32:35], v26 offset:33296
	v_cndmask_b32_e64 v16, v16, v17, s[44:45]
	s_waitcnt lgkmcnt(6)
	v_pk_fma_f32 v[108:109], v[36:37], v[8:9], v[116:117] op_sel_hi:[1,0,1]
	v_cvt_f16_f32_e32 v17, v16
	v_pk_fma_f32 v[110:111], v[38:39], v[8:9], v[118:119] op_sel_hi:[1,0,1]
	global_store_short v[98:99], v17, off
	v_pk_mul_f32 v[10:11], v[108:109], v[64:65]
	v_add_co_u32_e32 v98, vcc, 0x4000, v98
	v_pk_fma_f32 v[112:113], v[40:41], v[8:9], v[120:121] op_sel_hi:[1,0,1]
	v_pk_fma_f32 v[10:11], v[110:111], v[66:67], v[10:11]
	v_addc_co_u32_e32 v99, vcc, 0, v99, vcc
	v_pk_fma_f32 v[114:115], v[42:43], v[8:9], v[122:123] op_sel_hi:[1,0,1]
	v_pk_fma_f32 v[10:11], v[112:113], v[68:69], v[10:11]
	ds_read_b128 v[44:47], v26 offset:33792
	v_pk_fma_f32 v[10:11], v[114:115], v[70:71], v[10:11]
	ds_read_b128 v[48:51], v26 offset:33808
	v_add_f32_e32 v10, v10, v11
	ds_read_b32 v60, v27 offset:34304
	v_pk_fma_f32 v[116:117], v[96:97], v[80:81], v[108:109] op_sel_hi:[0,1,1]
	v_add_f32_dpp v10, v10, v10 quad_perm:[1,0,3,2] row_mask:0xf bank_mask:0xf bound_ctrl:1
	v_pk_fma_f32 v[118:119], v[96:97], v[82:83], v[110:111] op_sel_hi:[0,1,1]
	v_pk_fma_f32 v[120:121], v[96:97], v[84:85], v[112:113] op_sel_hi:[0,1,1]
	v_add_f32_dpp v10, v10, v10 quad_perm:[2,3,0,1] row_mask:0xf bank_mask:0xf bound_ctrl:1
	v_pk_fma_f32 v[122:123], v[96:97], v[86:87], v[114:115] op_sel_hi:[0,1,1]
	v_pk_mul_f32 v[12:13], v[52:53], v[108:109]
	v_add_f32_dpp v10, v10, v10 row_half_mirror row_mask:0xf bank_mask:0xf bound_ctrl:1
	v_pk_fma_f32 v[12:13], v[54:55], v[110:111], v[12:13]
	ds_read_b128 v[36:39], v26 offset:33536
	v_pk_fma_f32 v[12:13], v[56:57], v[112:113], v[12:13]
	ds_read_b128 v[40:43], v26 offset:33552
	v_pk_fma_f32 v[12:13], v[58:59], v[114:115], v[12:13]
	ds_read_b128 v[52:55], v26 offset:34048
	v_add_f32_e32 v100, v12, v13
	ds_read_b128 v[56:59], v26 offset:34064
	ds_read_b128 v[124:127], v26 offset:41728
	ds_read_b128 v[128:131], v26 offset:41744
	ds_read_b128 v[64:67], v26 offset:34560
	ds_read_b128 v[68:71], v26 offset:34576
	s_waitcnt lgkmcnt(11)
; __device__ __forceinline__ float sum8(float x) { x += dppf<0xB1>(x); x += dppf<0x4E>(x); x += dppf<0x141>(x); return x; }
; __global__ void __launch_bounds__(512, 2) fwd_megakernel(Params P) {
;     ...
;                                 for (int j = 0; j < 8; ++j) {
;                                     if (j < 7 || tt + 8 < 32) SCAN_LOAD(rg2[(j + 1) & 1], rv2[(j + 1) & 1], tt + j + 1);
;                                     __builtin_amdgcn_sched_barrier(0);
;                                     const f32x4 (&cur)[8] = rg2[j & 1]; const float curv = rv2[j & 1];
;                                     const f32x2 v2 = {curv, curv};
;                                     const f32x2 pa = v2 * cur[4].xy + Sa, pb = v2 * cur[4].zw + Sb, pc = v2 * cur[5].xy + Sc, pd = v2 * cur[5].zw + Sd;
;                                     f32x2 t0 = Sa * cur[0].xy; t0 = Sb * cur[0].zw + t0;
;                                     f32x2 t1 = Sc * cur[1].xy; t1 = Sd * cur[1].zw + t1;
;                                     const f32x2 t = t0 + t1;
;                                     float sa = sum8(t.x + t.y);
;                                     const f32x2 sa2 = {sa, sa};
;                                     Sa = sa2 * cur[2].xy + pa; Sb = sa2 * cur[2].zw + pb; Sc = sa2 * cur[3].xy + pc; Sd = sa2 * cur[3].zw + pd;
;                                     f32x2 u0 = Sa * cur[6].xy; u0 = Sb * cur[6].zw + u0;
;                                     f32x2 u1 = Sc * cur[7].xy; u1 = Sd * cur[7].zw + u1;
;                                     const f32x2 u = u0 + u1;
;                                     const float y = sum8(u.x + u.y);
;                                     yk = (kq == j) ? y : yk;
;                                 }
	v_pk_fma_f32 v[108:109], v[72:73], v[10:11], v[116:117] op_sel_hi:[1,0,1]
	v_pk_fma_f32 v[110:111], v[74:75], v[10:11], v[118:119] op_sel_hi:[1,0,1]
	v_pk_mul_f32 v[8:9], v[108:109], v[28:29]
	v_pk_fma_f32 v[112:113], v[76:77], v[10:11], v[120:121] op_sel_hi:[1,0,1]
	v_pk_fma_f32 v[8:9], v[110:111], v[30:31], v[8:9]
	v_pk_fma_f32 v[114:115], v[78:79], v[10:11], v[122:123] op_sel_hi:[1,0,1]
	v_pk_fma_f32 v[8:9], v[112:113], v[32:33], v[8:9]
	ds_read_b128 v[80:83], v26 offset:35072
	v_pk_fma_f32 v[8:9], v[114:115], v[34:35], v[8:9]
	ds_read_b128 v[84:87], v26 offset:35088
	v_add_f32_e32 v8, v8, v9
	ds_read_b32 v96, v27 offset:35584
	s_waitcnt lgkmcnt(11)
	v_pk_fma_f32 v[116:117], v[60:61], v[44:45], v[108:109] op_sel_hi:[0,1,1]
	v_add_f32_dpp v8, v8, v8 quad_perm:[1,0,3,2] row_mask:0xf bank_mask:0xf bound_ctrl:1
	v_pk_fma_f32 v[118:119], v[60:61], v[46:47], v[110:111] op_sel_hi:[0,1,1]
	v_pk_fma_f32 v[120:121], v[60:61], v[48:49], v[112:113] op_sel_hi:[0,1,1]
	v_add_f32_dpp v8, v8, v8 quad_perm:[2,3,0,1] row_mask:0xf bank_mask:0xf bound_ctrl:1
	v_pk_fma_f32 v[122:123], v[60:61], v[50:51], v[114:115] op_sel_hi:[0,1,1]
	v_pk_mul_f32 v[14:15], v[88:89], v[108:109]
	v_add_f32_dpp v8, v8, v8 row_half_mirror row_mask:0xf bank_mask:0xf bound_ctrl:1
	v_pk_fma_f32 v[14:15], v[90:91], v[110:111], v[14:15]
	ds_read_b128 v[72:75], v26 offset:34816
	v_pk_fma_f32 v[14:15], v[92:93], v[112:113], v[14:15]
	ds_read_b128 v[76:79], v26 offset:34832
	v_pk_fma_f32 v[14:15], v[94:95], v[114:115], v[14:15]
	ds_read_b128 v[88:91], v26 offset:35328
	v_add_f32_e32 v101, v14, v15
	ds_read_b128 v[92:95], v26 offset:35344
	v_add_f32_dpp v100, v100, v100 row_half_mirror row_mask:0xf bank_mask:0x5
	ds_read_b128 v[28:31], v26 offset:35840
	ds_read_b128 v[32:35], v26 offset:35856
	s_waitcnt lgkmcnt(9)
	v_pk_fma_f32 v[108:109], v[36:37], v[8:9], v[116:117] op_sel_hi:[1,0,1]
	v_pk_fma_f32 v[110:111], v[38:39], v[8:9], v[118:119] op_sel_hi:[1,0,1]
	v_pk_mul_f32 v[10:11], v[108:109], v[64:65]
	v_pk_fma_f32 v[112:113], v[40:41], v[8:9], v[120:121] op_sel_hi:[1,0,1]
	v_pk_fma_f32 v[10:11], v[110:111], v[66:67], v[10:11]
	v_pk_fma_f32 v[114:115], v[42:43], v[8:9], v[122:123] op_sel_hi:[1,0,1]
	v_pk_fma_f32 v[10:11], v[112:113], v[68:69], v[10:11]
	ds_read_b128 v[44:47], v26 offset:36352
	v_pk_fma_f32 v[10:11], v[114:115], v[70:71], v[10:11]
	ds_read_b128 v[48:51], v26 offset:36368
	v_add_f32_e32 v10, v10, v11
	ds_read_b32 v60, v27 offset:36864
	s_waitcnt lgkmcnt(9)
	v_pk_fma_f32 v[116:117], v[96:97], v[80:81], v[108:109] op_sel_hi:[0,1,1]
	v_add_f32_dpp v10, v10, v10 quad_perm:[1,0,3,2] row_mask:0xf bank_mask:0xf bound_ctrl:1
	v_pk_fma_f32 v[118:119], v[96:97], v[82:83], v[110:111] op_sel_hi:[0,1,1]
	v_pk_fma_f32 v[120:121], v[96:97], v[84:85], v[112:113] op_sel_hi:[0,1,1]
	v_add_f32_dpp v10, v10, v10 quad_perm:[2,3,0,1] row_mask:0xf bank_mask:0xf bound_ctrl:1
	v_pk_fma_f32 v[122:123], v[96:97], v[86:87], v[114:115] op_sel_hi:[0,1,1]
	v_pk_mul_f32 v[12:13], v[52:53], v[108:109]
	v_add_f32_dpp v10, v10, v10 row_half_mirror row_mask:0xf bank_mask:0xf bound_ctrl:1
	v_pk_fma_f32 v[12:13], v[54:55], v[110:111], v[12:13]
	ds_read_b128 v[36:39], v26 offset:36096
	v_pk_fma_f32 v[12:13], v[56:57], v[112:113], v[12:13]
	ds_read_b128 v[40:43], v26 offset:36112
	v_pk_fma_f32 v[12:13], v[58:59], v[114:115], v[12:13]
	ds_read_b128 v[52:55], v26 offset:36608
	v_add_f32_e32 v102, v12, v13
	ds_read_b128 v[56:59], v26 offset:36624
	v_add_f32_dpp v101, v101, v101 row_half_mirror row_mask:0xf bank_mask:0x5
	ds_read_b128 v[64:67], v26 offset:37120
	ds_read_b128 v[68:71], v26 offset:37136
	s_waitcnt lgkmcnt(9)
	v_pk_fma_f32 v[108:109], v[72:73], v[10:11], v[116:117] op_sel_hi:[1,0,1]
	v_pk_fma_f32 v[110:111], v[74:75], v[10:11], v[118:119] op_sel_hi:[1,0,1]
	v_pk_mul_f32 v[8:9], v[108:109], v[28:29]
	v_pk_fma_f32 v[112:113], v[76:77], v[10:11], v[120:121] op_sel_hi:[1,0,1]
	v_pk_fma_f32 v[8:9], v[110:111], v[30:31], v[8:9]
	v_pk_fma_f32 v[114:115], v[78:79], v[10:11], v[122:123] op_sel_hi:[1,0,1]
	v_pk_fma_f32 v[8:9], v[112:113], v[32:33], v[8:9]
	ds_read_b128 v[80:83], v26 offset:37632
	v_pk_fma_f32 v[8:9], v[114:115], v[34:35], v[8:9]
	ds_read_b128 v[84:87], v26 offset:37648
	v_add_f32_e32 v8, v8, v9
	ds_read_b32 v96, v27 offset:38144
	s_waitcnt lgkmcnt(9)
	v_pk_fma_f32 v[116:117], v[60:61], v[44:45], v[108:109] op_sel_hi:[0,1,1]
	v_add_f32_dpp v8, v8, v8 quad_perm:[1,0,3,2] row_mask:0xf bank_mask:0xf bound_ctrl:1
	v_pk_fma_f32 v[118:119], v[60:61], v[46:47], v[110:111] op_sel_hi:[0,1,1]
	v_pk_fma_f32 v[120:121], v[60:61], v[48:49], v[112:113] op_sel_hi:[0,1,1]
	v_add_f32_dpp v8, v8, v8 quad_perm:[2,3,0,1] row_mask:0xf bank_mask:0xf bound_ctrl:1
	v_pk_fma_f32 v[122:123], v[60:61], v[50:51], v[114:115] op_sel_hi:[0,1,1]
	v_pk_mul_f32 v[14:15], v[88:89], v[108:109]
	v_add_f32_dpp v8, v8, v8 row_half_mirror row_mask:0xf bank_mask:0xf bound_ctrl:1
	v_pk_fma_f32 v[14:15], v[90:91], v[110:111], v[14:15]
	ds_read_b128 v[72:75], v26 offset:37376
	v_pk_fma_f32 v[14:15], v[92:93], v[112:113], v[14:15]
	ds_read_b128 v[76:79], v26 offset:37392
	v_pk_fma_f32 v[14:15], v[94:95], v[114:115], v[14:15]
	ds_read_b128 v[88:91], v26 offset:37888
	v_add_f32_e32 v103, v14, v15
	ds_read_b128 v[92:95], v26 offset:37904
	v_add_f32_dpp v102, v102, v102 row_half_mirror row_mask:0xf bank_mask:0x5
	ds_read_b128 v[28:31], v26 offset:38400
	ds_read_b128 v[32:35], v26 offset:38416
	s_waitcnt lgkmcnt(9)
; __device__ __forceinline__ float sum8(float x) { x += dppf<0xB1>(x); x += dppf<0x4E>(x); x += dppf<0x141>(x); return x; }
; __global__ void __launch_bounds__(512, 2) fwd_megakernel(Params P) {
;     ...
;                                 for (int j = 0; j < 8; ++j) {
;                                     if (j < 7 || tt + 8 < 32) SCAN_LOAD(rg2[(j + 1) & 1], rv2[(j + 1) & 1], tt + j + 1);
;                                     __builtin_amdgcn_sched_barrier(0);
;                                     const f32x4 (&cur)[8] = rg2[j & 1]; const float curv = rv2[j & 1];
;                                     const f32x2 v2 = {curv, curv};
;                                     const f32x2 pa = v2 * cur[4].xy + Sa, pb = v2 * cur[4].zw + Sb, pc = v2 * cur[5].xy + Sc, pd = v2 * cur[5].zw + Sd;
;                                     f32x2 t0 = Sa * cur[0].xy; t0 = Sb * cur[0].zw + t0;
;                                     f32x2 t1 = Sc * cur[1].xy; t1 = Sd * cur[1].zw + t1;
;                                     const f32x2 t = t0 + t1;
;                                     float sa = sum8(t.x + t.y);
;                                     const f32x2 sa2 = {sa, sa};
;                                     Sa = sa2 * cur[2].xy + pa; Sb = sa2 * cur[2].zw + pb; Sc = sa2 * cur[3].xy + pc; Sd = sa2 * cur[3].zw + pd;
;                                     f32x2 u0 = Sa * cur[6].xy; u0 = Sb * cur[6].zw + u0;
;                                     f32x2 u1 = Sc * cur[7].xy; u1 = Sd * cur[7].zw + u1;
;                                     const f32x2 u = u0 + u1;
;                                     const float y = sum8(u.x + u.y);
;                                     yk = (kq == j) ? y : yk;
;                                 }
	v_pk_fma_f32 v[108:109], v[36:37], v[8:9], v[116:117] op_sel_hi:[1,0,1]
	v_pk_fma_f32 v[110:111], v[38:39], v[8:9], v[118:119] op_sel_hi:[1,0,1]
	v_pk_mul_f32 v[10:11], v[108:109], v[64:65]
	v_pk_fma_f32 v[112:113], v[40:41], v[8:9], v[120:121] op_sel_hi:[1,0,1]
	v_pk_fma_f32 v[10:11], v[110:111], v[66:67], v[10:11]
	v_pk_fma_f32 v[114:115], v[42:43], v[8:9], v[122:123] op_sel_hi:[1,0,1]
	v_pk_fma_f32 v[10:11], v[112:113], v[68:69], v[10:11]
	ds_read_b128 v[44:47], v26 offset:38912
	v_pk_fma_f32 v[10:11], v[114:115], v[70:71], v[10:11]
	ds_read_b128 v[48:51], v26 offset:38928
	v_add_f32_e32 v10, v10, v11
	ds_read_b32 v60, v27 offset:39424
	s_waitcnt lgkmcnt(9)
	v_pk_fma_f32 v[116:117], v[96:97], v[80:81], v[108:109] op_sel_hi:[0,1,1]
	v_add_f32_dpp v10, v10, v10 quad_perm:[1,0,3,2] row_mask:0xf bank_mask:0xf bound_ctrl:1
	v_pk_fma_f32 v[118:119], v[96:97], v[82:83], v[110:111] op_sel_hi:[0,1,1]
	v_pk_fma_f32 v[120:121], v[96:97], v[84:85], v[112:113] op_sel_hi:[0,1,1]
	v_add_f32_dpp v10, v10, v10 quad_perm:[2,3,0,1] row_mask:0xf bank_mask:0xf bound_ctrl:1
	v_pk_fma_f32 v[122:123], v[96:97], v[86:87], v[114:115] op_sel_hi:[0,1,1]
	v_pk_mul_f32 v[12:13], v[52:53], v[108:109]
	v_add_f32_dpp v10, v10, v10 row_half_mirror row_mask:0xf bank_mask:0xf bound_ctrl:1
	v_pk_fma_f32 v[12:13], v[54:55], v[110:111], v[12:13]
	ds_read_b128 v[36:39], v26 offset:38656
	v_pk_fma_f32 v[12:13], v[56:57], v[112:113], v[12:13]
	ds_read_b128 v[40:43], v26 offset:38672
	v_pk_fma_f32 v[12:13], v[58:59], v[114:115], v[12:13]
	ds_read_b128 v[52:55], v26 offset:39168
	v_add_f32_e32 v104, v12, v13
	ds_read_b128 v[56:59], v26 offset:39184
	v_add_f32_dpp v103, v103, v103 row_half_mirror row_mask:0xf bank_mask:0x5
	v_add_f32_dpp v100, v104, v104 row_half_mirror row_mask:0xf bank_mask:0xa
	ds_read_b128 v[64:67], v26 offset:39680
	ds_read_b128 v[68:71], v26 offset:39696
	s_waitcnt lgkmcnt(9)
	v_pk_fma_f32 v[108:109], v[72:73], v[10:11], v[116:117] op_sel_hi:[1,0,1]
	v_pk_fma_f32 v[110:111], v[74:75], v[10:11], v[118:119] op_sel_hi:[1,0,1]
	v_pk_mul_f32 v[8:9], v[108:109], v[28:29]
	v_pk_fma_f32 v[112:113], v[76:77], v[10:11], v[120:121] op_sel_hi:[1,0,1]
	v_pk_fma_f32 v[8:9], v[110:111], v[30:31], v[8:9]
	v_pk_fma_f32 v[114:115], v[78:79], v[10:11], v[122:123] op_sel_hi:[1,0,1]
	v_pk_fma_f32 v[8:9], v[112:113], v[32:33], v[8:9]
	ds_read_b128 v[80:83], v26 offset:40192
	v_pk_fma_f32 v[8:9], v[114:115], v[34:35], v[8:9]
	ds_read_b128 v[84:87], v26 offset:40208
	v_add_f32_e32 v8, v8, v9
	ds_read_b32 v96, v27 offset:40704
	s_waitcnt lgkmcnt(9)
	v_pk_fma_f32 v[116:117], v[60:61], v[44:45], v[108:109] op_sel_hi:[0,1,1]
	v_add_f32_dpp v8, v8, v8 quad_perm:[1,0,3,2] row_mask:0xf bank_mask:0xf bound_ctrl:1
	v_pk_fma_f32 v[118:119], v[60:61], v[46:47], v[110:111] op_sel_hi:[0,1,1]
	v_pk_fma_f32 v[120:121], v[60:61], v[48:49], v[112:113] op_sel_hi:[0,1,1]
	v_add_f32_dpp v8, v8, v8 quad_perm:[2,3,0,1] row_mask:0xf bank_mask:0xf bound_ctrl:1
	v_pk_fma_f32 v[122:123], v[60:61], v[50:51], v[114:115] op_sel_hi:[0,1,1]
	v_pk_mul_f32 v[14:15], v[88:89], v[108:109]
	v_add_f32_dpp v8, v8, v8 row_half_mirror row_mask:0xf bank_mask:0xf bound_ctrl:1
	v_pk_fma_f32 v[14:15], v[90:91], v[110:111], v[14:15]
	ds_read_b128 v[72:75], v26 offset:39936
	v_pk_fma_f32 v[14:15], v[92:93], v[112:113], v[14:15]
	ds_read_b128 v[76:79], v26 offset:39952
	v_pk_fma_f32 v[14:15], v[94:95], v[114:115], v[14:15]
	ds_read_b128 v[88:91], v26 offset:40448
	v_add_f32_e32 v105, v14, v15
	ds_read_b128 v[92:95], v26 offset:40464
	s_waitcnt lgkmcnt(0)
	s_barrier
; #define LAS __attribute__((address_space(3)))
; __device__ __forceinline__ float sum8(float x) { x += dppf<0xB1>(x); x += dppf<0x4E>(x); x += dppf<0x141>(x); return x; }
; __global__ void __launch_bounds__(512, 2) fwd_megakernel(Params P) {
;     ...
;                             for (int tt = 0; tt < 32; tt += 8) {
;                                 float yk = 0.f;
;                                 const f32x4 ge0 = *(const LAS f32x4*)(pk + 40960 + (tt >> 3) * 256), ge1 = *(const LAS f32x4*)(pk + 40960 + (tt >> 3) * 256 + 16);
; #pragma unroll
;                                 for (int j = 0; j < 8; ++j) {
;                                     if (j < 7 || tt + 8 < 32) SCAN_LOAD(rg2[(j + 1) & 1], rv2[(j + 1) & 1], tt + j + 1);
;                                     __builtin_amdgcn_sched_barrier(0);
;                                     const f32x4 (&cur)[8] = rg2[j & 1]; const float curv = rv2[j & 1];
;                                     const f32x2 v2 = {curv, curv};
;                                     const f32x2 pa = v2 * cur[4].xy + Sa, pb = v2 * cur[4].zw + Sb, pc = v2 * cur[5].xy + Sc, pd = v2 * cur[5].zw + Sd;
;                                     f32x2 t0 = Sa * cur[0].xy; t0 = Sb * cur[0].zw + t0;
;                                     f32x2 t1 = Sc * cur[1].xy; t1 = Sd * cur[1].zw + t1;
;                                     const f32x2 t = t0 + t1;
;                                     float sa = sum8(t.x + t.y);
;                                     const f32x2 sa2 = {sa, sa};
;                                     Sa = sa2 * cur[2].xy + pa; Sb = sa2 * cur[2].zw + pb; Sc = sa2 * cur[3].xy + pc; Sd = sa2 * cur[3].zw + pd;
;                                     f32x2 u0 = Sa * cur[6].xy; u0 = Sb * cur[6].zw + u0;
;                                     f32x2 u1 = Sc * cur[7].xy; u1 = Sd * cur[7].zw + u1;
;                                     const f32x2 u = u0 + u1;
;                                     const float y = sum8(u.x + u.y);
;                                     yk = (kq == j) ? y : yk;
;                                 }
;                                 Sa *= ge0.xy; Sb *= ge0.zw; Sc *= ge1.xy; Sd *= ge1.zw;
;                                 yout[(size_t)(c * 32 + tt + kq) * 1024] = (f16)yk;
;                             }
;                             __syncthreads();
	v_add_f32_dpp v101, v105, v105 row_half_mirror row_mask:0xf bank_mask:0xa
	v_xor_b32_e32 v26, 0xa400, v26
	v_xor_b32_e32 v27, 0xa400, v27
	v_pk_fma_f32 v[108:109], v[36:37], v[8:9], v[116:117] op_sel_hi:[1,0,1]
	ds_read_b128 v[140:143], v26 offset:0
	ds_read_b128 v[144:147], v26 offset:16
	ds_read_b128 v[156:159], v26 offset:512
	ds_read_b128 v[160:163], v26 offset:528
	ds_read_b32 v172, v27 offset:1024
	ds_read_b128 v[148:151], v26 offset:256
	ds_read_b128 v[152:155], v26 offset:272
	ds_read_b128 v[164:167], v26 offset:768
	ds_read_b128 v[168:171], v26 offset:784
	v_pk_fma_f32 v[110:111], v[38:39], v[8:9], v[118:119] op_sel_hi:[1,0,1]
	v_pk_mul_f32 v[10:11], v[108:109], v[64:65]
	v_pk_fma_f32 v[112:113], v[40:41], v[8:9], v[120:121] op_sel_hi:[1,0,1]
	v_pk_fma_f32 v[10:11], v[110:111], v[66:67], v[10:11]
	v_pk_fma_f32 v[114:115], v[42:43], v[8:9], v[122:123] op_sel_hi:[1,0,1]
	v_pk_fma_f32 v[10:11], v[112:113], v[68:69], v[10:11]
	v_pk_fma_f32 v[116:117], v[96:97], v[80:81], v[108:109] op_sel_hi:[0,1,1]
	v_pk_fma_f32 v[10:11], v[114:115], v[70:71], v[10:11]
	v_pk_fma_f32 v[118:119], v[96:97], v[82:83], v[110:111] op_sel_hi:[0,1,1]
	v_add_f32_e32 v10, v10, v11
	v_pk_fma_f32 v[120:121], v[96:97], v[84:85], v[112:113] op_sel_hi:[0,1,1]
	v_pk_fma_f32 v[122:123], v[96:97], v[86:87], v[114:115] op_sel_hi:[0,1,1]
	v_add_f32_dpp v10, v10, v10 quad_perm:[1,0,3,2] row_mask:0xf bank_mask:0xf bound_ctrl:1
	v_pk_mul_f32 v[12:13], v[52:53], v[108:109]
	v_add_f32_dpp v16, v100, v100 quad_perm:[2,3,0,1] row_mask:0xf bank_mask:0xf bound_ctrl:1
	v_add_f32_dpp v10, v10, v10 quad_perm:[2,3,0,1] row_mask:0xf bank_mask:0xf bound_ctrl:1
	v_pk_fma_f32 v[12:13], v[54:55], v[110:111], v[12:13]
	v_add_f32_dpp v62, v101, v101 quad_perm:[2,3,0,1] row_mask:0xf bank_mask:0xf bound_ctrl:1
	v_add_f32_dpp v10, v10, v10 row_half_mirror row_mask:0xf bank_mask:0xf bound_ctrl:1
	v_pk_fma_f32 v[12:13], v[56:57], v[112:113], v[12:13]
	v_pk_fma_f32 v[108:109], v[72:73], v[10:11], v[116:117] op_sel_hi:[1,0,1]
	v_pk_fma_f32 v[12:13], v[58:59], v[114:115], v[12:13]
	v_pk_fma_f32 v[110:111], v[74:75], v[10:11], v[118:119] op_sel_hi:[1,0,1]
	v_add_f32_e32 v106, v12, v13
	v_pk_fma_f32 v[112:113], v[76:77], v[10:11], v[120:121] op_sel_hi:[1,0,1]
	v_pk_fma_f32 v[114:115], v[78:79], v[10:11], v[122:123] op_sel_hi:[1,0,1]
	v_add_f32_dpp v102, v106, v106 row_half_mirror row_mask:0xf bank_mask:0xa
	v_pk_mul_f32 v[18:19], v[124:125], v[108:109]
	v_pk_mul_f32 v[20:21], v[126:127], v[110:111]
	v_pk_mul_f32 v[22:23], v[128:129], v[112:113]
	v_pk_mul_f32 v[24:25], v[130:131], v[114:115]
	v_pk_mul_f32 v[14:15], v[88:89], v[108:109]
	v_add_f32_dpp v17, v102, v102 quad_perm:[2,3,0,1] row_mask:0xf bank_mask:0xf bound_ctrl:1
	v_pk_fma_f32 v[14:15], v[90:91], v[110:111], v[14:15]
	v_cndmask_b32_e64 v61, v16, v17, s[100:101]
	v_pk_fma_f32 v[14:15], v[92:93], v[112:113], v[14:15]
	s_nop 0
	v_pk_fma_f32 v[14:15], v[94:95], v[114:115], v[14:15]
	v_add_f32_dpp v16, v61, v61 quad_perm:[1,0,3,2] row_mask:0xf bank_mask:0xf bound_ctrl:1
	v_add_f32_e32 v107, v14, v15
	s_nop 1
	v_add_f32_dpp v103, v107, v107 row_half_mirror row_mask:0xf bank_mask:0xa
	s_nop 1
	v_add_f32_dpp v63, v103, v103 quad_perm:[2,3,0,1] row_mask:0xf bank_mask:0xf bound_ctrl:1
	s_nop 0
	v_cndmask_b32_e64 v97, v62, v63, s[100:101]
	s_nop 1
	v_add_f32_dpp v17, v97, v97 quad_perm:[1,0,3,2] row_mask:0xf bank_mask:0xf bound_ctrl:1
	s_nop 0
	v_cndmask_b32_e64 v16, v16, v17, s[44:45]
	s_nop 0
	v_cvt_f16_f32_e32 v17, v16
	s_nop 0
	global_store_short v[98:99], v17, off
	s_nop 0
	v_add_co_u32_e32 v98, vcc, 0x4000, v98
	s_nop 1
	v_addc_co_u32_e32 v99, vcc, 0, v99, vcc
	s_add_u32 s94, s94, 0x10000
	s_cmp_eq_u32 s94, 0x800000
	s_cbranch_scc0 .Lscan_chunk
	s_waitcnt lgkmcnt(0)
	s_setprio 0
	s_mov_b64 s[62:63], 0
